# all 10 standard kloops: glds pieces interleaved after each 4-MFMA group of k-step 0
# speedup vs baseline: 1.0102x; 1.0024x over previous
.LBB0_53:
	s_cmp_eq_u32 s40, 0x70000
	s_mov_b32 s29, 0x10000
	s_cbranch_scc1 .LBB0_52
	s_and_b32 s29, s40, 0x10000
	s_add_i32 s29, s29, 0
	v_add3_u32 v149, s29, v138, v139
	ds_read_b128 v[150:153], v149 offset:32768
	ds_read_b128 v[154:157], v149 offset:34816
	ds_read_b128 v[162:165], v149 offset:36864
	ds_read_b128 v[166:169], v149 offset:38912
	v_add3_u32 v174, s29, v138, v140
	ds_read_b128 v[158:161], v174
	v_add3_u32 v175, s29, v142, v141
	v_add3_u32 v189, s29, v142, v143
	v_add3_u32 v198, s29, v142, v144
	ds_read_b128 v[170:173], v175
	s_waitcnt lgkmcnt(1)
	v_mfma_f32_16x16x32_bf16 v[126:129], v[150:153], v[158:161], v[126:129]
	v_add3_u32 v199, s29, v142, v145
	v_add3_u32 v200, s29, v142, v146
	v_add3_u32 v201, s29, v142, v147
	v_mfma_f32_16x16x32_bf16 v[122:125], v[154:157], v[158:161], v[122:125]
	v_add3_u32 v202, s29, v142, v148
	v_mfma_f32_16x16x32_bf16 v[118:121], v[162:165], v[158:161], v[118:121]
	v_mfma_f32_16x16x32_bf16 v[114:117], v[166:169], v[158:161], v[114:117]
	ds_read_b128 v[158:161], v189
	ds_read_b128 v[190:193], v198
	s_and_b32 s29, s40, 0x10000
	s_xor_b32 s39, s29, 0x10000
	s_add_i32 s43, s39, s41
	s_mov_b32 m0, s43
	s_nop 0
	global_load_lds_dwordx4 v131, s[6:7]
	s_waitcnt lgkmcnt(2)
	v_mfma_f32_16x16x32_bf16 v[110:113], v[150:153], v[170:173], v[110:113]
	v_mfma_f32_16x16x32_bf16 v[106:109], v[154:157], v[170:173], v[106:109]
	v_mfma_f32_16x16x32_bf16 v[102:105], v[162:165], v[170:173], v[102:105]
	v_mfma_f32_16x16x32_bf16 v[98:101], v[166:169], v[170:173], v[98:101]
	ds_read_b128 v[170:173], v199
	ds_read_b128 v[194:197], v200
	s_add_i32 s39, s39, s42
	s_mov_b32 m0, s39
	s_nop 0
	global_load_lds_dwordx4 v130, s[8:9]
	s_waitcnt lgkmcnt(3)
	v_mfma_f32_16x16x32_bf16 v[94:97], v[150:153], v[158:161], v[94:97]
	v_mfma_f32_16x16x32_bf16 v[90:93], v[154:157], v[158:161], v[90:93]
	v_mfma_f32_16x16x32_bf16 v[86:89], v[162:165], v[158:161], v[86:89]
	v_mfma_f32_16x16x32_bf16 v[82:85], v[166:169], v[158:161], v[82:85]
	s_xor_b32 s39, s29, 0x12000
	s_add_i32 s43, s39, s41
	s_add_i32 s39, s39, s42
	s_mov_b32 m0, s43
	s_nop 0
	global_load_lds_dwordx4 v135, s[6:7]
	s_waitcnt lgkmcnt(2)
	v_mfma_f32_16x16x32_bf16 v[78:81], v[150:153], v[190:193], v[78:81]
	v_mfma_f32_16x16x32_bf16 v[74:77], v[154:157], v[190:193], v[74:77]
	v_mfma_f32_16x16x32_bf16 v[70:73], v[162:165], v[190:193], v[70:73]
	v_mfma_f32_16x16x32_bf16 v[66:69], v[166:169], v[190:193], v[66:69]
	ds_read_b128 v[158:161], v201
	ds_read_b128 v[190:193], v202
	s_add_u32 s46, s8, 0x20000
	s_addc_u32 s47, s9, 0
	s_mov_b32 m0, s39
	s_nop 0
	global_load_lds_dwordx4 v130, s[46:47]
	s_waitcnt lgkmcnt(3)
	v_mfma_f32_16x16x32_bf16 v[62:65], v[150:153], v[170:173], v[62:65]
	v_mfma_f32_16x16x32_bf16 v[58:61], v[154:157], v[170:173], v[58:61]
	v_mfma_f32_16x16x32_bf16 v[54:57], v[162:165], v[170:173], v[54:57]
	v_mfma_f32_16x16x32_bf16 v[50:53], v[166:169], v[170:173], v[50:53]
	s_xor_b32 s39, s29, 0x14000
	s_add_i32 s43, s39, s41
	s_add_i32 s39, s39, s42
	s_mov_b32 m0, s43
	s_nop 0
	global_load_lds_dwordx4 v136, s[6:7]
	s_waitcnt lgkmcnt(2)
	v_mfma_f32_16x16x32_bf16 v[46:49], v[150:153], v[194:197], v[46:49]
	v_mfma_f32_16x16x32_bf16 v[42:45], v[154:157], v[194:197], v[42:45]
	v_mfma_f32_16x16x32_bf16 v[38:41], v[162:165], v[194:197], v[38:41]
	v_mfma_f32_16x16x32_bf16 v[34:37], v[166:169], v[194:197], v[34:37]
	s_add_u32 s46, s8, 0x40000
	s_addc_u32 s47, s9, 0
	s_mov_b32 m0, s39
	s_nop 0
	global_load_lds_dwordx4 v130, s[46:47]
	s_waitcnt lgkmcnt(1)
	v_mfma_f32_16x16x32_bf16 v[30:33], v[150:153], v[158:161], v[30:33]
	v_mfma_f32_16x16x32_bf16 v[26:29], v[154:157], v[158:161], v[26:29]
	v_mfma_f32_16x16x32_bf16 v[22:25], v[162:165], v[158:161], v[22:25]
	v_mfma_f32_16x16x32_bf16 v[18:21], v[166:169], v[158:161], v[18:21]
	s_xor_b32 s39, s29, 0x16000
	s_add_i32 s43, s39, s41
	s_add_i32 s39, s39, s42
	s_mov_b32 m0, s43
	s_nop 0
	global_load_lds_dwordx4 v137, s[6:7]
	s_waitcnt lgkmcnt(0)
	v_mfma_f32_16x16x32_bf16 v[14:17], v[150:153], v[190:193], v[14:17]
	v_mfma_f32_16x16x32_bf16 v[10:13], v[154:157], v[190:193], v[10:13]
	v_mfma_f32_16x16x32_bf16 v[6:9], v[162:165], v[190:193], v[6:9]
	v_mfma_f32_16x16x32_bf16 v[2:5], v[166:169], v[190:193], v[2:5]
	ds_read_b128 v[150:153], v149 offset:33792
	ds_read_b128 v[154:157], v149 offset:35840
	ds_read_b128 v[162:165], v149 offset:37888
	ds_read_b128 v[166:169], v149 offset:39936
	ds_read_b128 v[158:161], v174 offset:1024
	ds_read_b128 v[170:173], v175 offset:1024
	s_add_u32 s46, s8, 0x60000
	s_addc_u32 s47, s9, 0
	s_mov_b32 m0, s39
	s_nop 0
	global_load_lds_dwordx4 v130, s[46:47]
	s_waitcnt lgkmcnt(1)
	v_mfma_f32_16x16x32_bf16 v[126:129], v[150:153], v[158:161], v[126:129]
	v_mfma_f32_16x16x32_bf16 v[122:125], v[154:157], v[158:161], v[122:125]
	v_mfma_f32_16x16x32_bf16 v[118:121], v[162:165], v[158:161], v[118:121]
	v_mfma_f32_16x16x32_bf16 v[114:117], v[166:169], v[158:161], v[114:117]
	ds_read_b128 v[158:161], v189 offset:1024
	ds_read_b128 v[190:193], v198 offset:1024
	s_waitcnt lgkmcnt(2)
	v_mfma_f32_16x16x32_bf16 v[110:113], v[150:153], v[170:173], v[110:113]
	v_mfma_f32_16x16x32_bf16 v[106:109], v[154:157], v[170:173], v[106:109]
	v_mfma_f32_16x16x32_bf16 v[102:105], v[162:165], v[170:173], v[102:105]
	v_mfma_f32_16x16x32_bf16 v[98:101], v[166:169], v[170:173], v[98:101]
	ds_read_b128 v[170:173], v199 offset:1024
	ds_read_b128 v[194:197], v200 offset:1024
	s_waitcnt lgkmcnt(3)
	v_mfma_f32_16x16x32_bf16 v[94:97], v[150:153], v[158:161], v[94:97]
	v_mfma_f32_16x16x32_bf16 v[90:93], v[154:157], v[158:161], v[90:93]
	v_mfma_f32_16x16x32_bf16 v[86:89], v[162:165], v[158:161], v[86:89]
	v_mfma_f32_16x16x32_bf16 v[82:85], v[166:169], v[158:161], v[82:85]
	s_waitcnt lgkmcnt(2)
	v_mfma_f32_16x16x32_bf16 v[78:81], v[150:153], v[190:193], v[78:81]
	v_mfma_f32_16x16x32_bf16 v[74:77], v[154:157], v[190:193], v[74:77]
	v_mfma_f32_16x16x32_bf16 v[70:73], v[162:165], v[190:193], v[70:73]
	v_mfma_f32_16x16x32_bf16 v[66:69], v[166:169], v[190:193], v[66:69]
	ds_read_b128 v[158:161], v201 offset:1024
	ds_read_b128 v[190:193], v202 offset:1024
	s_waitcnt lgkmcnt(3)
	v_mfma_f32_16x16x32_bf16 v[62:65], v[150:153], v[170:173], v[62:65]
	v_mfma_f32_16x16x32_bf16 v[58:61], v[154:157], v[170:173], v[58:61]
	v_mfma_f32_16x16x32_bf16 v[54:57], v[162:165], v[170:173], v[54:57]
	v_mfma_f32_16x16x32_bf16 v[50:53], v[166:169], v[170:173], v[50:53]
	s_waitcnt lgkmcnt(2)
	v_mfma_f32_16x16x32_bf16 v[46:49], v[150:153], v[194:197], v[46:49]
	v_mfma_f32_16x16x32_bf16 v[42:45], v[154:157], v[194:197], v[42:45]
	v_mfma_f32_16x16x32_bf16 v[38:41], v[162:165], v[194:197], v[38:41]
	v_mfma_f32_16x16x32_bf16 v[34:37], v[166:169], v[194:197], v[34:37]
	s_waitcnt lgkmcnt(1)
	v_mfma_f32_16x16x32_bf16 v[30:33], v[150:153], v[158:161], v[30:33]
	v_mfma_f32_16x16x32_bf16 v[26:29], v[154:157], v[158:161], v[26:29]
	v_mfma_f32_16x16x32_bf16 v[22:25], v[162:165], v[158:161], v[22:25]
	v_mfma_f32_16x16x32_bf16 v[18:21], v[166:169], v[158:161], v[18:21]
	s_waitcnt lgkmcnt(0)
	v_mfma_f32_16x16x32_bf16 v[14:17], v[150:153], v[190:193], v[14:17]
	v_mfma_f32_16x16x32_bf16 v[10:13], v[154:157], v[190:193], v[10:13]
	v_mfma_f32_16x16x32_bf16 v[6:9], v[162:165], v[190:193], v[6:9]
	v_mfma_f32_16x16x32_bf16 v[2:5], v[166:169], v[190:193], v[2:5]
	s_add_i32 s40, s40, 0x10000
	s_add_u32 s6, s6, 0x80
	s_addc_u32 s7, s7, 0
	s_waitcnt vmcnt(0)
	s_add_u32 s8, s8, 0x80
	s_addc_u32 s9, s9, 0
	s_cmp_lg_u32 s40, 0x80000
	s_barrier
	s_cbranch_scc0 .LBB0_50
	s_branch .LBB0_53

.LBB0_60:
	s_and_b32 s46, s41, 1
	s_lshl_b32 s29, s46, 16
	s_cmp_lt_u32 s41, 3
	s_cbranch_scc0 .LBB0_59
	s_add_i32 s18, s29, 0
	v_add3_u32 v149, s18, v138, v139
	ds_read_b128 v[150:153], v149 offset:32768
	ds_read_b128 v[154:157], v149 offset:34816
	ds_read_b128 v[162:165], v149 offset:36864
	ds_read_b128 v[166:169], v149 offset:38912
	v_add3_u32 v174, s18, v138, v140
	ds_read_b128 v[158:161], v174
	v_add3_u32 v175, s18, v142, v141
	v_add3_u32 v189, s18, v142, v143
	v_add3_u32 v198, s18, v142, v144
	ds_read_b128 v[170:173], v175
	s_waitcnt lgkmcnt(1)
	v_mfma_f32_16x16x32_bf16 v[126:129], v[150:153], v[158:161], v[126:129]
	v_add3_u32 v199, s18, v142, v145
	v_add3_u32 v200, s18, v142, v146
	v_add3_u32 v201, s18, v142, v147
	v_mfma_f32_16x16x32_bf16 v[122:125], v[154:157], v[158:161], v[122:125]
	v_add3_u32 v202, s18, v142, v148
	s_add_i32 s41, s41, 1
	v_mfma_f32_16x16x32_bf16 v[118:121], v[162:165], v[158:161], v[118:121]
	v_mfma_f32_16x16x32_bf16 v[114:117], v[166:169], v[158:161], v[114:117]
	ds_read_b128 v[158:161], v189
	ds_read_b128 v[190:193], v198
	s_lshl_b32 s29, s46, 16
	s_xor_b32 s18, s29, 0x10000
	s_add_i32 s19, s18, s42
	s_mov_b32 m0, s19
	s_nop 0
	global_load_lds_dwordx4 v134, s[12:13]
	s_waitcnt lgkmcnt(2)
	v_mfma_f32_16x16x32_bf16 v[110:113], v[150:153], v[170:173], v[110:113]
	v_mfma_f32_16x16x32_bf16 v[106:109], v[154:157], v[170:173], v[106:109]
	v_mfma_f32_16x16x32_bf16 v[102:105], v[162:165], v[170:173], v[102:105]
	v_mfma_f32_16x16x32_bf16 v[98:101], v[166:169], v[170:173], v[98:101]
	ds_read_b128 v[170:173], v199
	ds_read_b128 v[194:197], v200
	s_add_i32 s18, s18, s43
	s_mov_b32 m0, s18
	s_nop 0
	global_load_lds_dwordx4 v133, s[16:17]
	s_waitcnt lgkmcnt(3)
	v_mfma_f32_16x16x32_bf16 v[94:97], v[150:153], v[158:161], v[94:97]
	v_mfma_f32_16x16x32_bf16 v[90:93], v[154:157], v[158:161], v[90:93]
	v_mfma_f32_16x16x32_bf16 v[86:89], v[162:165], v[158:161], v[86:89]
	v_mfma_f32_16x16x32_bf16 v[82:85], v[166:169], v[158:161], v[82:85]
	s_xor_b32 s18, s29, 0x12000
	s_add_i32 s19, s18, s42
	s_add_i32 s39, s18, s43
	s_mov_b32 m0, s19
	s_nop 0
	global_load_lds_dwordx4 v135, s[12:13]
	s_waitcnt lgkmcnt(2)
	v_mfma_f32_16x16x32_bf16 v[78:81], v[150:153], v[190:193], v[78:81]
	v_mfma_f32_16x16x32_bf16 v[74:77], v[154:157], v[190:193], v[74:77]
	v_mfma_f32_16x16x32_bf16 v[70:73], v[162:165], v[190:193], v[70:73]
	v_mfma_f32_16x16x32_bf16 v[66:69], v[166:169], v[190:193], v[66:69]
	ds_read_b128 v[158:161], v201
	ds_read_b128 v[190:193], v202
	s_add_u32 s18, s16, 0x8000
	s_addc_u32 s19, s17, 0
	s_mov_b32 m0, s39
	s_nop 0
	global_load_lds_dwordx4 v133, s[18:19]
	s_waitcnt lgkmcnt(3)
	v_mfma_f32_16x16x32_bf16 v[62:65], v[150:153], v[170:173], v[62:65]
	v_mfma_f32_16x16x32_bf16 v[58:61], v[154:157], v[170:173], v[58:61]
	v_mfma_f32_16x16x32_bf16 v[54:57], v[162:165], v[170:173], v[54:57]
	v_mfma_f32_16x16x32_bf16 v[50:53], v[166:169], v[170:173], v[50:53]
	s_xor_b32 s18, s29, 0x14000
	s_add_i32 s19, s18, s42
	s_add_i32 s39, s18, s43
	s_mov_b32 m0, s19
	s_nop 0
	global_load_lds_dwordx4 v136, s[12:13]
	s_waitcnt lgkmcnt(2)
	v_mfma_f32_16x16x32_bf16 v[46:49], v[150:153], v[194:197], v[46:49]
	v_mfma_f32_16x16x32_bf16 v[42:45], v[154:157], v[194:197], v[42:45]
	v_mfma_f32_16x16x32_bf16 v[38:41], v[162:165], v[194:197], v[38:41]
	v_mfma_f32_16x16x32_bf16 v[34:37], v[166:169], v[194:197], v[34:37]
	s_add_u32 s18, s16, 0x10000
	s_addc_u32 s19, s17, 0
	s_mov_b32 m0, s39
	s_nop 0
	global_load_lds_dwordx4 v133, s[18:19]
	s_waitcnt lgkmcnt(1)
	v_mfma_f32_16x16x32_bf16 v[30:33], v[150:153], v[158:161], v[30:33]
	v_mfma_f32_16x16x32_bf16 v[26:29], v[154:157], v[158:161], v[26:29]
	v_mfma_f32_16x16x32_bf16 v[22:25], v[162:165], v[158:161], v[22:25]
	v_mfma_f32_16x16x32_bf16 v[18:21], v[166:169], v[158:161], v[18:21]
	s_xor_b32 s18, s29, 0x16000
	s_add_i32 s19, s18, s42
	s_add_i32 s39, s18, s43
	s_mov_b32 m0, s19
	s_nop 0
	global_load_lds_dwordx4 v137, s[12:13]
	s_waitcnt lgkmcnt(0)
	v_mfma_f32_16x16x32_bf16 v[14:17], v[150:153], v[190:193], v[14:17]
	v_mfma_f32_16x16x32_bf16 v[10:13], v[154:157], v[190:193], v[10:13]
	v_mfma_f32_16x16x32_bf16 v[6:9], v[162:165], v[190:193], v[6:9]
	v_mfma_f32_16x16x32_bf16 v[2:5], v[166:169], v[190:193], v[2:5]
	ds_read_b128 v[150:153], v149 offset:33792
	ds_read_b128 v[154:157], v149 offset:35840
	ds_read_b128 v[162:165], v149 offset:37888
	ds_read_b128 v[166:169], v149 offset:39936
	ds_read_b128 v[158:161], v174 offset:1024
	ds_read_b128 v[170:173], v175 offset:1024
	s_add_u32 s18, s16, 0x18000
	s_addc_u32 s19, s17, 0
	s_mov_b32 m0, s39
	s_nop 0
	global_load_lds_dwordx4 v133, s[18:19]
	s_waitcnt lgkmcnt(1)
	v_mfma_f32_16x16x32_bf16 v[126:129], v[150:153], v[158:161], v[126:129]
	v_mfma_f32_16x16x32_bf16 v[122:125], v[154:157], v[158:161], v[122:125]
	v_mfma_f32_16x16x32_bf16 v[118:121], v[162:165], v[158:161], v[118:121]
	v_mfma_f32_16x16x32_bf16 v[114:117], v[166:169], v[158:161], v[114:117]
	ds_read_b128 v[158:161], v189 offset:1024
	ds_read_b128 v[190:193], v198 offset:1024
	s_waitcnt lgkmcnt(2)
	v_mfma_f32_16x16x32_bf16 v[110:113], v[150:153], v[170:173], v[110:113]
	v_mfma_f32_16x16x32_bf16 v[106:109], v[154:157], v[170:173], v[106:109]
	v_mfma_f32_16x16x32_bf16 v[102:105], v[162:165], v[170:173], v[102:105]
	v_mfma_f32_16x16x32_bf16 v[98:101], v[166:169], v[170:173], v[98:101]
	ds_read_b128 v[170:173], v199 offset:1024
	ds_read_b128 v[194:197], v200 offset:1024
	s_waitcnt lgkmcnt(3)
	v_mfma_f32_16x16x32_bf16 v[94:97], v[150:153], v[158:161], v[94:97]
	v_mfma_f32_16x16x32_bf16 v[90:93], v[154:157], v[158:161], v[90:93]
	v_mfma_f32_16x16x32_bf16 v[86:89], v[162:165], v[158:161], v[86:89]
	v_mfma_f32_16x16x32_bf16 v[82:85], v[166:169], v[158:161], v[82:85]
	s_waitcnt lgkmcnt(2)
	v_mfma_f32_16x16x32_bf16 v[78:81], v[150:153], v[190:193], v[78:81]
	v_mfma_f32_16x16x32_bf16 v[74:77], v[154:157], v[190:193], v[74:77]
	v_mfma_f32_16x16x32_bf16 v[70:73], v[162:165], v[190:193], v[70:73]
	v_mfma_f32_16x16x32_bf16 v[66:69], v[166:169], v[190:193], v[66:69]
	ds_read_b128 v[158:161], v201 offset:1024
	ds_read_b128 v[190:193], v202 offset:1024
	s_waitcnt lgkmcnt(3)
	v_mfma_f32_16x16x32_bf16 v[62:65], v[150:153], v[170:173], v[62:65]
	v_mfma_f32_16x16x32_bf16 v[58:61], v[154:157], v[170:173], v[58:61]
	v_mfma_f32_16x16x32_bf16 v[54:57], v[162:165], v[170:173], v[54:57]
	v_mfma_f32_16x16x32_bf16 v[50:53], v[166:169], v[170:173], v[50:53]
	s_waitcnt lgkmcnt(2)
	v_mfma_f32_16x16x32_bf16 v[46:49], v[150:153], v[194:197], v[46:49]
	v_mfma_f32_16x16x32_bf16 v[42:45], v[154:157], v[194:197], v[42:45]
	v_mfma_f32_16x16x32_bf16 v[38:41], v[162:165], v[194:197], v[38:41]
	v_mfma_f32_16x16x32_bf16 v[34:37], v[166:169], v[194:197], v[34:37]
	s_waitcnt lgkmcnt(1)
	v_mfma_f32_16x16x32_bf16 v[30:33], v[150:153], v[158:161], v[30:33]
	v_mfma_f32_16x16x32_bf16 v[26:29], v[154:157], v[158:161], v[26:29]
	v_mfma_f32_16x16x32_bf16 v[22:25], v[162:165], v[158:161], v[22:25]
	v_mfma_f32_16x16x32_bf16 v[18:21], v[166:169], v[158:161], v[18:21]
	s_waitcnt lgkmcnt(0)
	v_mfma_f32_16x16x32_bf16 v[14:17], v[150:153], v[190:193], v[14:17]
	v_mfma_f32_16x16x32_bf16 v[10:13], v[154:157], v[190:193], v[10:13]
	v_mfma_f32_16x16x32_bf16 v[6:9], v[162:165], v[190:193], v[6:9]
	v_mfma_f32_16x16x32_bf16 v[2:5], v[166:169], v[190:193], v[2:5]
	s_add_u32 s16, s16, 0x80
	s_addc_u32 s17, s17, 0
	s_waitcnt vmcnt(0)
	s_add_u32 s12, s12, 0x80
	s_addc_u32 s13, s13, 0
	s_cmp_lg_u32 s41, 4
	s_barrier
	s_cbranch_scc0 .LBB0_57
	s_branch .LBB0_60

.LBB0_72:
	s_and_b32 s43, s40, 1
	s_lshl_b32 s29, s43, 16
	s_cmp_lt_u32 s40, 15
	s_cbranch_scc0 .LBB0_71
	s_add_i32 s20, s29, 0
	v_add3_u32 v174, s20, v135, v136
	ds_read_b128 v[150:153], v174 offset:32768
	ds_read_b128 v[154:157], v174 offset:34816
	ds_read_b128 v[162:165], v174 offset:36864
	ds_read_b128 v[166:169], v174 offset:38912
	v_add3_u32 v175, s20, v135, v137
	ds_read_b128 v[158:161], v175
	v_add3_u32 v189, s20, v139, v138
	v_add3_u32 v198, s20, v139, v140
	v_add3_u32 v199, s20, v139, v141
	ds_read_b128 v[170:173], v189
	s_waitcnt lgkmcnt(1)
	v_mfma_f32_16x16x32_bf16 v[122:125], v[150:153], v[158:161], v[122:125]
	v_add3_u32 v200, s20, v139, v146
	v_add3_u32 v201, s20, v139, v147
	v_add3_u32 v202, s20, v139, v148
	v_mfma_f32_16x16x32_bf16 v[126:129], v[154:157], v[158:161], v[126:129]
	v_add3_u32 v203, s20, v139, v149
	s_add_i32 s40, s40, 1
	v_mfma_f32_16x16x32_bf16 v[114:117], v[162:165], v[158:161], v[114:117]
	v_mfma_f32_16x16x32_bf16 v[118:121], v[166:169], v[158:161], v[118:121]
	ds_read_b128 v[158:161], v198
	ds_read_b128 v[190:193], v199
	s_lshl_b32 s29, s43, 16
	s_xor_b32 s20, s29, 0x10000
	s_add_i32 s21, s20, s41
	s_mov_b32 m0, s21
	s_nop 0
	global_load_lds_dwordx4 v131, s[16:17]
	s_waitcnt lgkmcnt(2)
	v_mfma_f32_16x16x32_bf16 v[106:109], v[150:153], v[170:173], v[106:109]
	v_mfma_f32_16x16x32_bf16 v[110:113], v[154:157], v[170:173], v[110:113]
	v_mfma_f32_16x16x32_bf16 v[98:101], v[162:165], v[170:173], v[98:101]
	v_mfma_f32_16x16x32_bf16 v[102:105], v[166:169], v[170:173], v[102:105]
	ds_read_b128 v[170:173], v200
	ds_read_b128 v[194:197], v201
	s_add_i32 s20, s20, s42
	s_mov_b32 m0, s20
	s_nop 0
	global_load_lds_dwordx4 v130, s[18:19]
	s_waitcnt lgkmcnt(3)
	v_mfma_f32_16x16x32_bf16 v[86:89], v[150:153], v[158:161], v[86:89]
	v_mfma_f32_16x16x32_bf16 v[94:97], v[154:157], v[158:161], v[94:97]
	v_mfma_f32_16x16x32_bf16 v[82:85], v[162:165], v[158:161], v[82:85]
	v_mfma_f32_16x16x32_bf16 v[90:93], v[166:169], v[158:161], v[90:93]
	s_xor_b32 s20, s29, 0x12000
	s_add_i32 s21, s20, s41
	s_add_i32 s39, s20, s42
	s_mov_b32 m0, s21
	s_nop 0
	global_load_lds_dwordx4 v132, s[16:17]
	s_waitcnt lgkmcnt(2)
	v_mfma_f32_16x16x32_bf16 v[70:73], v[150:153], v[190:193], v[70:73]
	v_mfma_f32_16x16x32_bf16 v[78:81], v[154:157], v[190:193], v[78:81]
	v_mfma_f32_16x16x32_bf16 v[66:69], v[162:165], v[190:193], v[66:69]
	v_mfma_f32_16x16x32_bf16 v[74:77], v[166:169], v[190:193], v[74:77]
	ds_read_b128 v[158:161], v202
	ds_read_b128 v[190:193], v203
	s_add_u32 s20, s18, 0x20000
	s_addc_u32 s21, s19, 0
	s_mov_b32 m0, s39
	s_nop 0
	global_load_lds_dwordx4 v130, s[20:21]
	s_waitcnt lgkmcnt(3)
	v_mfma_f32_16x16x32_bf16 v[54:57], v[150:153], v[170:173], v[54:57]
	v_mfma_f32_16x16x32_bf16 v[62:65], v[154:157], v[170:173], v[62:65]
	v_mfma_f32_16x16x32_bf16 v[50:53], v[162:165], v[170:173], v[50:53]
	v_mfma_f32_16x16x32_bf16 v[58:61], v[166:169], v[170:173], v[58:61]
	s_xor_b32 s20, s29, 0x14000
	s_add_i32 s21, s20, s41
	s_add_i32 s39, s20, s42
	s_mov_b32 m0, s21
	s_nop 0
	global_load_lds_dwordx4 v133, s[16:17]
	s_waitcnt lgkmcnt(2)
	v_mfma_f32_16x16x32_bf16 v[38:41], v[150:153], v[194:197], v[38:41]
	v_mfma_f32_16x16x32_bf16 v[46:49], v[154:157], v[194:197], v[46:49]
	v_mfma_f32_16x16x32_bf16 v[34:37], v[162:165], v[194:197], v[34:37]
	v_mfma_f32_16x16x32_bf16 v[42:45], v[166:169], v[194:197], v[42:45]
	s_add_u32 s20, s18, 0x40000
	s_addc_u32 s21, s19, 0
	s_mov_b32 m0, s39
	s_nop 0
	global_load_lds_dwordx4 v130, s[20:21]
	s_waitcnt lgkmcnt(1)
	v_mfma_f32_16x16x32_bf16 v[22:25], v[150:153], v[158:161], v[22:25]
	v_mfma_f32_16x16x32_bf16 v[30:33], v[154:157], v[158:161], v[30:33]
	v_mfma_f32_16x16x32_bf16 v[18:21], v[162:165], v[158:161], v[18:21]
	v_mfma_f32_16x16x32_bf16 v[26:29], v[166:169], v[158:161], v[26:29]
	s_xor_b32 s20, s29, 0x16000
	s_add_i32 s21, s20, s41
	s_add_i32 s39, s20, s42
	s_mov_b32 m0, s21
	s_nop 0
	global_load_lds_dwordx4 v134, s[16:17]
	s_waitcnt lgkmcnt(0)
	v_mfma_f32_16x16x32_bf16 v[6:9], v[150:153], v[190:193], v[6:9]
	v_mfma_f32_16x16x32_bf16 v[14:17], v[154:157], v[190:193], v[14:17]
	v_mfma_f32_16x16x32_bf16 v[2:5], v[162:165], v[190:193], v[2:5]
	v_mfma_f32_16x16x32_bf16 v[10:13], v[166:169], v[190:193], v[10:13]
	ds_read_b128 v[150:153], v174 offset:33792
	ds_read_b128 v[154:157], v174 offset:35840
	ds_read_b128 v[162:165], v174 offset:37888
	ds_read_b128 v[166:169], v174 offset:39936
	ds_read_b128 v[158:161], v175 offset:1024
	ds_read_b128 v[170:173], v189 offset:1024
	s_add_u32 s20, s18, 0x60000
	s_addc_u32 s21, s19, 0
	s_mov_b32 m0, s39
	s_nop 0
	global_load_lds_dwordx4 v130, s[20:21]
	s_waitcnt lgkmcnt(1)
	v_mfma_f32_16x16x32_bf16 v[122:125], v[150:153], v[158:161], v[122:125]
	v_mfma_f32_16x16x32_bf16 v[126:129], v[154:157], v[158:161], v[126:129]
	v_mfma_f32_16x16x32_bf16 v[114:117], v[162:165], v[158:161], v[114:117]
	v_mfma_f32_16x16x32_bf16 v[118:121], v[166:169], v[158:161], v[118:121]
	ds_read_b128 v[158:161], v198 offset:1024
	ds_read_b128 v[190:193], v199 offset:1024
	s_waitcnt lgkmcnt(2)
	v_mfma_f32_16x16x32_bf16 v[106:109], v[150:153], v[170:173], v[106:109]
	v_mfma_f32_16x16x32_bf16 v[110:113], v[154:157], v[170:173], v[110:113]
	v_mfma_f32_16x16x32_bf16 v[98:101], v[162:165], v[170:173], v[98:101]
	v_mfma_f32_16x16x32_bf16 v[102:105], v[166:169], v[170:173], v[102:105]
	ds_read_b128 v[170:173], v200 offset:1024
	ds_read_b128 v[194:197], v201 offset:1024
	s_waitcnt lgkmcnt(3)
	v_mfma_f32_16x16x32_bf16 v[86:89], v[150:153], v[158:161], v[86:89]
	v_mfma_f32_16x16x32_bf16 v[94:97], v[154:157], v[158:161], v[94:97]
	v_mfma_f32_16x16x32_bf16 v[82:85], v[162:165], v[158:161], v[82:85]
	v_mfma_f32_16x16x32_bf16 v[90:93], v[166:169], v[158:161], v[90:93]
	s_waitcnt lgkmcnt(2)
	v_mfma_f32_16x16x32_bf16 v[70:73], v[150:153], v[190:193], v[70:73]
	v_mfma_f32_16x16x32_bf16 v[78:81], v[154:157], v[190:193], v[78:81]
	v_mfma_f32_16x16x32_bf16 v[66:69], v[162:165], v[190:193], v[66:69]
	v_mfma_f32_16x16x32_bf16 v[74:77], v[166:169], v[190:193], v[74:77]
	ds_read_b128 v[158:161], v202 offset:1024
	ds_read_b128 v[190:193], v203 offset:1024
	s_waitcnt lgkmcnt(3)
	v_mfma_f32_16x16x32_bf16 v[54:57], v[150:153], v[170:173], v[54:57]
	v_mfma_f32_16x16x32_bf16 v[62:65], v[154:157], v[170:173], v[62:65]
	v_mfma_f32_16x16x32_bf16 v[50:53], v[162:165], v[170:173], v[50:53]
	v_mfma_f32_16x16x32_bf16 v[58:61], v[166:169], v[170:173], v[58:61]
	s_waitcnt lgkmcnt(2)
	v_mfma_f32_16x16x32_bf16 v[38:41], v[150:153], v[194:197], v[38:41]
	v_mfma_f32_16x16x32_bf16 v[46:49], v[154:157], v[194:197], v[46:49]
	v_mfma_f32_16x16x32_bf16 v[34:37], v[162:165], v[194:197], v[34:37]
	v_mfma_f32_16x16x32_bf16 v[42:45], v[166:169], v[194:197], v[42:45]
	s_waitcnt lgkmcnt(1)
	v_mfma_f32_16x16x32_bf16 v[22:25], v[150:153], v[158:161], v[22:25]
	v_mfma_f32_16x16x32_bf16 v[30:33], v[154:157], v[158:161], v[30:33]
	v_mfma_f32_16x16x32_bf16 v[18:21], v[162:165], v[158:161], v[18:21]
	v_mfma_f32_16x16x32_bf16 v[26:29], v[166:169], v[158:161], v[26:29]
	s_waitcnt lgkmcnt(0)
	v_mfma_f32_16x16x32_bf16 v[6:9], v[150:153], v[190:193], v[6:9]
	v_mfma_f32_16x16x32_bf16 v[14:17], v[154:157], v[190:193], v[14:17]
	v_mfma_f32_16x16x32_bf16 v[2:5], v[162:165], v[190:193], v[2:5]
	v_mfma_f32_16x16x32_bf16 v[10:13], v[166:169], v[190:193], v[10:13]
	s_add_u32 s18, s18, 0x80
	s_addc_u32 s19, s19, 0
	s_waitcnt vmcnt(0)
	s_add_u32 s16, s16, 0x80
	s_addc_u32 s17, s17, 0
	s_cmp_lg_u32 s40, 16
	s_barrier
	s_cbranch_scc0 .LBB0_76
	s_branch .LBB0_72

.LBB0_107:
	s_and_b32 s68, s30, 1
	s_lshl_b32 s29, s68, 16
	s_cmp_lt_u32 s30, 3
	s_cbranch_scc0 .LBB0_106
	s_add_i32 s10, s29, 0
	v_add3_u32 v174, s10, v139, v141
	ds_read_b128 v[162:165], v174 offset:32768
	ds_read_b128 v[166:169], v174 offset:34816
	ds_read_b128 v[190:193], v174 offset:36864
	ds_read_b128 v[194:197], v174 offset:38912
	v_add3_u32 v175, s10, v139, v143
	ds_read_b128 v[170:173], v175
	v_add3_u32 v189, s10, v145, v144
	v_add3_u32 v210, s10, v145, v146
	v_add3_u32 v211, s10, v145, v147
	ds_read_b128 v[198:201], v189
	s_waitcnt lgkmcnt(1)
	v_mfma_f32_16x16x32_bf16 v[126:129], v[162:165], v[170:173], v[126:129]
	v_add3_u32 v212, s10, v145, v148
	v_add3_u32 v213, s10, v145, v149
	v_add3_u32 v214, s10, v145, v150
	v_mfma_f32_16x16x32_bf16 v[122:125], v[166:169], v[170:173], v[122:125]
	v_add3_u32 v215, s10, v145, v151
	s_add_i32 s30, s30, 1
	v_mfma_f32_16x16x32_bf16 v[118:121], v[190:193], v[170:173], v[118:121]
	v_mfma_f32_16x16x32_bf16 v[114:117], v[194:197], v[170:173], v[114:117]
	ds_read_b128 v[170:173], v210
	ds_read_b128 v[202:205], v211
	s_add_u32 s10, s2, s8
	s_addc_u32 s11, s3, s9
	s_add_u32 s46, s6, s8
	s_addc_u32 s47, s7, s9
	s_lshl_b32 s29, s68, 16
	s_xor_b32 s39, s29, 0x10000
	s_add_i32 s68, s39, s66
	s_mov_b32 m0, s68
	s_nop 0
	global_load_lds_dwordx4 v131, s[10:11]
	s_waitcnt lgkmcnt(2)
	v_mfma_f32_16x16x32_bf16 v[110:113], v[162:165], v[198:201], v[110:113]
	v_mfma_f32_16x16x32_bf16 v[106:109], v[166:169], v[198:201], v[106:109]
	v_mfma_f32_16x16x32_bf16 v[102:105], v[190:193], v[198:201], v[102:105]
	v_mfma_f32_16x16x32_bf16 v[98:101], v[194:197], v[198:201], v[98:101]
	ds_read_b128 v[198:201], v212
	ds_read_b128 v[206:209], v213
	s_add_i32 s39, s39, s67
	s_mov_b32 m0, s39
	s_nop 0
	global_load_lds_dwordx4 v130, s[46:47]
	s_waitcnt lgkmcnt(3)
	v_mfma_f32_16x16x32_bf16 v[94:97], v[162:165], v[170:173], v[94:97]
	v_mfma_f32_16x16x32_bf16 v[90:93], v[166:169], v[170:173], v[90:93]
	v_mfma_f32_16x16x32_bf16 v[86:89], v[190:193], v[170:173], v[86:89]
	v_mfma_f32_16x16x32_bf16 v[82:85], v[194:197], v[170:173], v[82:85]
	s_xor_b32 s39, s29, 0x12000
	s_add_i32 s68, s39, s66
	s_add_i32 s39, s39, s67
	s_mov_b32 m0, s68
	s_nop 0
	global_load_lds_dwordx4 v132, s[10:11]
	s_waitcnt lgkmcnt(2)
	v_mfma_f32_16x16x32_bf16 v[78:81], v[162:165], v[202:205], v[78:81]
	v_mfma_f32_16x16x32_bf16 v[74:77], v[166:169], v[202:205], v[74:77]
	v_mfma_f32_16x16x32_bf16 v[70:73], v[190:193], v[202:205], v[70:73]
	v_mfma_f32_16x16x32_bf16 v[66:69], v[194:197], v[202:205], v[66:69]
	ds_read_b128 v[170:173], v214
	ds_read_b128 v[202:205], v215
	s_add_u32 s68, s46, 0x8000
	s_addc_u32 s69, s47, 0
	s_mov_b32 m0, s39
	s_nop 0
	global_load_lds_dwordx4 v130, s[68:69]
	s_waitcnt lgkmcnt(3)
	v_mfma_f32_16x16x32_bf16 v[62:65], v[162:165], v[198:201], v[62:65]
	v_mfma_f32_16x16x32_bf16 v[58:61], v[166:169], v[198:201], v[58:61]
	v_mfma_f32_16x16x32_bf16 v[54:57], v[190:193], v[198:201], v[54:57]
	v_mfma_f32_16x16x32_bf16 v[50:53], v[194:197], v[198:201], v[50:53]
	s_xor_b32 s39, s29, 0x14000
	s_add_i32 s68, s39, s66
	s_add_i32 s39, s39, s67
	s_mov_b32 m0, s68
	s_nop 0
	global_load_lds_dwordx4 v133, s[10:11]
	s_waitcnt lgkmcnt(2)
	v_mfma_f32_16x16x32_bf16 v[46:49], v[162:165], v[206:209], v[46:49]
	v_mfma_f32_16x16x32_bf16 v[42:45], v[166:169], v[206:209], v[42:45]
	v_mfma_f32_16x16x32_bf16 v[38:41], v[190:193], v[206:209], v[38:41]
	v_mfma_f32_16x16x32_bf16 v[34:37], v[194:197], v[206:209], v[34:37]
	s_add_u32 s68, s46, 0x10000
	s_addc_u32 s69, s47, 0
	s_mov_b32 m0, s39
	s_nop 0
	global_load_lds_dwordx4 v130, s[68:69]
	s_waitcnt lgkmcnt(1)
	v_mfma_f32_16x16x32_bf16 v[30:33], v[162:165], v[170:173], v[30:33]
	v_mfma_f32_16x16x32_bf16 v[26:29], v[166:169], v[170:173], v[26:29]
	v_mfma_f32_16x16x32_bf16 v[22:25], v[190:193], v[170:173], v[22:25]
	v_mfma_f32_16x16x32_bf16 v[18:21], v[194:197], v[170:173], v[18:21]
	s_xor_b32 s39, s29, 0x16000
	s_add_i32 s68, s39, s66
	s_add_i32 s39, s39, s67
	s_mov_b32 m0, s68
	s_nop 0
	global_load_lds_dwordx4 v135, s[10:11]
	s_waitcnt lgkmcnt(0)
	v_mfma_f32_16x16x32_bf16 v[14:17], v[162:165], v[202:205], v[14:17]
	v_mfma_f32_16x16x32_bf16 v[10:13], v[166:169], v[202:205], v[10:13]
	v_mfma_f32_16x16x32_bf16 v[6:9], v[190:193], v[202:205], v[6:9]
	v_mfma_f32_16x16x32_bf16 v[2:5], v[194:197], v[202:205], v[2:5]
	ds_read_b128 v[162:165], v174 offset:33792
	ds_read_b128 v[166:169], v174 offset:35840
	ds_read_b128 v[190:193], v174 offset:37888
	ds_read_b128 v[194:197], v174 offset:39936
	ds_read_b128 v[170:173], v175 offset:1024
	ds_read_b128 v[198:201], v189 offset:1024
	s_add_u32 s10, s46, 0x18000
	s_addc_u32 s11, s47, 0
	s_mov_b32 m0, s39
	s_nop 0
	global_load_lds_dwordx4 v130, s[10:11]
	s_waitcnt lgkmcnt(1)
	v_mfma_f32_16x16x32_bf16 v[126:129], v[162:165], v[170:173], v[126:129]
	v_mfma_f32_16x16x32_bf16 v[122:125], v[166:169], v[170:173], v[122:125]
	v_mfma_f32_16x16x32_bf16 v[118:121], v[190:193], v[170:173], v[118:121]
	v_mfma_f32_16x16x32_bf16 v[114:117], v[194:197], v[170:173], v[114:117]
	ds_read_b128 v[170:173], v210 offset:1024
	ds_read_b128 v[202:205], v211 offset:1024
	s_waitcnt lgkmcnt(2)
	v_mfma_f32_16x16x32_bf16 v[110:113], v[162:165], v[198:201], v[110:113]
	v_mfma_f32_16x16x32_bf16 v[106:109], v[166:169], v[198:201], v[106:109]
	v_mfma_f32_16x16x32_bf16 v[102:105], v[190:193], v[198:201], v[102:105]
	v_mfma_f32_16x16x32_bf16 v[98:101], v[194:197], v[198:201], v[98:101]
	ds_read_b128 v[198:201], v212 offset:1024
	ds_read_b128 v[206:209], v213 offset:1024
	s_waitcnt lgkmcnt(3)
	v_mfma_f32_16x16x32_bf16 v[94:97], v[162:165], v[170:173], v[94:97]
	v_mfma_f32_16x16x32_bf16 v[90:93], v[166:169], v[170:173], v[90:93]
	v_mfma_f32_16x16x32_bf16 v[86:89], v[190:193], v[170:173], v[86:89]
	v_mfma_f32_16x16x32_bf16 v[82:85], v[194:197], v[170:173], v[82:85]
	s_waitcnt lgkmcnt(2)
	v_mfma_f32_16x16x32_bf16 v[78:81], v[162:165], v[202:205], v[78:81]
	v_mfma_f32_16x16x32_bf16 v[74:77], v[166:169], v[202:205], v[74:77]
	v_mfma_f32_16x16x32_bf16 v[70:73], v[190:193], v[202:205], v[70:73]
	v_mfma_f32_16x16x32_bf16 v[66:69], v[194:197], v[202:205], v[66:69]
	ds_read_b128 v[170:173], v214 offset:1024
	ds_read_b128 v[202:205], v215 offset:1024
	s_waitcnt lgkmcnt(3)
	v_mfma_f32_16x16x32_bf16 v[62:65], v[162:165], v[198:201], v[62:65]
	v_mfma_f32_16x16x32_bf16 v[58:61], v[166:169], v[198:201], v[58:61]
	v_mfma_f32_16x16x32_bf16 v[54:57], v[190:193], v[198:201], v[54:57]
	v_mfma_f32_16x16x32_bf16 v[50:53], v[194:197], v[198:201], v[50:53]
	s_waitcnt lgkmcnt(2)
	v_mfma_f32_16x16x32_bf16 v[46:49], v[162:165], v[206:209], v[46:49]
	v_mfma_f32_16x16x32_bf16 v[42:45], v[166:169], v[206:209], v[42:45]
	v_mfma_f32_16x16x32_bf16 v[38:41], v[190:193], v[206:209], v[38:41]
	v_mfma_f32_16x16x32_bf16 v[34:37], v[194:197], v[206:209], v[34:37]
	s_waitcnt lgkmcnt(1)
	v_mfma_f32_16x16x32_bf16 v[30:33], v[162:165], v[170:173], v[30:33]
	v_mfma_f32_16x16x32_bf16 v[26:29], v[166:169], v[170:173], v[26:29]
	v_mfma_f32_16x16x32_bf16 v[22:25], v[190:193], v[170:173], v[22:25]
	v_mfma_f32_16x16x32_bf16 v[18:21], v[194:197], v[170:173], v[18:21]
	s_waitcnt lgkmcnt(0)
	v_mfma_f32_16x16x32_bf16 v[14:17], v[162:165], v[202:205], v[14:17]
	v_mfma_f32_16x16x32_bf16 v[10:13], v[166:169], v[202:205], v[10:13]
	v_mfma_f32_16x16x32_bf16 v[6:9], v[190:193], v[202:205], v[6:9]
	v_mfma_f32_16x16x32_bf16 v[2:5], v[194:197], v[202:205], v[2:5]
	s_waitcnt vmcnt(0)
	s_add_u32 s8, s8, 0x80
	s_addc_u32 s9, s9, 0
	s_cmp_lg_u32 s30, 4
	s_barrier
	s_cbranch_scc0 .LBB0_111
	s_branch .LBB0_107

.LBB0_203:
	s_and_b32 s21, s9, 1
	s_lshl_b32 s19, s21, 16
	s_cmp_lt_u32 s9, 15
	s_cbranch_scc0 .LBB0_202
	s_add_i32 s10, s19, 0
	v_add3_u32 v191, s10, v131, v132
	ds_read_b128 v[146:149], v191 offset:32768
	ds_read_b128 v[150:153], v191 offset:34816
	ds_read_b128 v[158:161], v191 offset:36864
	ds_read_b128 v[162:165], v191 offset:38912
	v_add3_u32 v196, s10, v131, v133
	ds_read_b128 v[154:157], v196
	v_add3_u32 v197, s10, v135, v134
	v_add3_u32 v198, s10, v135, v136
	v_add3_u32 v199, s10, v135, v137
	ds_read_b128 v[166:169], v197
	s_waitcnt lgkmcnt(1)
	v_mfma_f32_16x16x32_bf16 v[142:145], v[146:149], v[154:157], v[142:145]
	v_add3_u32 v200, s10, v135, v138
	v_add3_u32 v201, s10, v135, v139
	v_add3_u32 v202, s10, v135, v140
	v_mfma_f32_16x16x32_bf16 v[122:125], v[150:153], v[154:157], v[122:125]
	v_add3_u32 v203, s10, v135, v141
	s_add_i32 s9, s9, 1
	v_mfma_f32_16x16x32_bf16 v[118:121], v[158:161], v[154:157], v[118:121]
	v_mfma_f32_16x16x32_bf16 v[114:117], v[162:165], v[154:157], v[114:117]
	ds_read_b128 v[154:157], v198
	ds_read_b128 v[170:173], v199
	s_lshl_b32 s19, s21, 16
	s_xor_b32 s10, s19, 0x10000
	s_add_i32 s11, s10, s17
	s_mov_b32 m0, s11
	s_nop 0
	global_load_lds_dwordx4 v127, s[2:3]
	s_waitcnt lgkmcnt(2)
	v_mfma_f32_16x16x32_bf16 v[110:113], v[146:149], v[166:169], v[110:113]
	v_mfma_f32_16x16x32_bf16 v[106:109], v[150:153], v[166:169], v[106:109]
	v_mfma_f32_16x16x32_bf16 v[102:105], v[158:161], v[166:169], v[102:105]
	v_mfma_f32_16x16x32_bf16 v[98:101], v[162:165], v[166:169], v[98:101]
	ds_read_b128 v[166:169], v200
	ds_read_b128 v[192:195], v201
	s_add_i32 s10, s10, s18
	s_mov_b32 m0, s10
	s_nop 0
	global_load_lds_dwordx4 v126, s[6:7]
	s_waitcnt lgkmcnt(3)
	v_mfma_f32_16x16x32_bf16 v[94:97], v[146:149], v[154:157], v[94:97]
	v_mfma_f32_16x16x32_bf16 v[90:93], v[150:153], v[154:157], v[90:93]
	v_mfma_f32_16x16x32_bf16 v[86:89], v[158:161], v[154:157], v[86:89]
	v_mfma_f32_16x16x32_bf16 v[82:85], v[162:165], v[154:157], v[82:85]
	s_xor_b32 s10, s19, 0x12000
	s_add_i32 s11, s10, s17
	s_add_i32 s21, s10, s18
	s_mov_b32 m0, s11
	s_nop 0
	global_load_lds_dwordx4 v128, s[2:3]
	s_waitcnt lgkmcnt(2)
	v_mfma_f32_16x16x32_bf16 v[78:81], v[146:149], v[170:173], v[78:81]
	v_mfma_f32_16x16x32_bf16 v[74:77], v[150:153], v[170:173], v[74:77]
	v_mfma_f32_16x16x32_bf16 v[70:73], v[158:161], v[170:173], v[70:73]
	v_mfma_f32_16x16x32_bf16 v[66:69], v[162:165], v[170:173], v[66:69]
	ds_read_b128 v[154:157], v202
	ds_read_b128 v[170:173], v203
	s_add_u32 s10, s6, 0x20000
	s_addc_u32 s11, s7, 0
	s_mov_b32 m0, s21
	s_nop 0
	global_load_lds_dwordx4 v126, s[10:11]
	s_waitcnt lgkmcnt(3)
	v_mfma_f32_16x16x32_bf16 v[62:65], v[146:149], v[166:169], v[62:65]
	v_mfma_f32_16x16x32_bf16 v[58:61], v[150:153], v[166:169], v[58:61]
	v_mfma_f32_16x16x32_bf16 v[54:57], v[158:161], v[166:169], v[54:57]
	v_mfma_f32_16x16x32_bf16 v[50:53], v[162:165], v[166:169], v[50:53]
	s_xor_b32 s10, s19, 0x14000
	s_add_i32 s11, s10, s17
	s_add_i32 s21, s10, s18
	s_mov_b32 m0, s11
	s_nop 0
	global_load_lds_dwordx4 v129, s[2:3]
	s_waitcnt lgkmcnt(2)
	v_mfma_f32_16x16x32_bf16 v[46:49], v[146:149], v[192:195], v[46:49]
	v_mfma_f32_16x16x32_bf16 v[42:45], v[150:153], v[192:195], v[42:45]
	v_mfma_f32_16x16x32_bf16 v[38:41], v[158:161], v[192:195], v[38:41]
	v_mfma_f32_16x16x32_bf16 v[34:37], v[162:165], v[192:195], v[34:37]
	s_add_u32 s10, s6, 0x40000
	s_addc_u32 s11, s7, 0
	s_mov_b32 m0, s21
	s_nop 0
	global_load_lds_dwordx4 v126, s[10:11]
	s_waitcnt lgkmcnt(1)
	v_mfma_f32_16x16x32_bf16 v[30:33], v[146:149], v[154:157], v[30:33]
	v_mfma_f32_16x16x32_bf16 v[26:29], v[150:153], v[154:157], v[26:29]
	v_mfma_f32_16x16x32_bf16 v[22:25], v[158:161], v[154:157], v[22:25]
	v_mfma_f32_16x16x32_bf16 v[18:21], v[162:165], v[154:157], v[18:21]
	s_xor_b32 s10, s19, 0x16000
	s_add_i32 s11, s10, s17
	s_add_i32 s21, s10, s18
	s_mov_b32 m0, s11
	s_nop 0
	global_load_lds_dwordx4 v130, s[2:3]
	s_waitcnt lgkmcnt(0)
	v_mfma_f32_16x16x32_bf16 v[14:17], v[146:149], v[170:173], v[14:17]
	v_mfma_f32_16x16x32_bf16 v[10:13], v[150:153], v[170:173], v[10:13]
	v_mfma_f32_16x16x32_bf16 v[6:9], v[158:161], v[170:173], v[6:9]
	v_mfma_f32_16x16x32_bf16 v[2:5], v[162:165], v[170:173], v[2:5]
	ds_read_b128 v[146:149], v191 offset:33792
	ds_read_b128 v[150:153], v191 offset:35840
	ds_read_b128 v[158:161], v191 offset:37888
	ds_read_b128 v[162:165], v191 offset:39936
	ds_read_b128 v[154:157], v196 offset:1024
	ds_read_b128 v[166:169], v197 offset:1024
	s_add_u32 s10, s6, 0x60000
	s_addc_u32 s11, s7, 0
	s_mov_b32 m0, s21
	s_nop 0
	global_load_lds_dwordx4 v126, s[10:11]
	s_waitcnt lgkmcnt(1)
	v_mfma_f32_16x16x32_bf16 v[142:145], v[146:149], v[154:157], v[142:145]
	v_mfma_f32_16x16x32_bf16 v[122:125], v[150:153], v[154:157], v[122:125]
	v_mfma_f32_16x16x32_bf16 v[118:121], v[158:161], v[154:157], v[118:121]
	v_mfma_f32_16x16x32_bf16 v[114:117], v[162:165], v[154:157], v[114:117]
	ds_read_b128 v[154:157], v198 offset:1024
	ds_read_b128 v[170:173], v199 offset:1024
	s_waitcnt lgkmcnt(2)
	v_mfma_f32_16x16x32_bf16 v[110:113], v[146:149], v[166:169], v[110:113]
	v_mfma_f32_16x16x32_bf16 v[106:109], v[150:153], v[166:169], v[106:109]
	v_mfma_f32_16x16x32_bf16 v[102:105], v[158:161], v[166:169], v[102:105]
	v_mfma_f32_16x16x32_bf16 v[98:101], v[162:165], v[166:169], v[98:101]
	ds_read_b128 v[166:169], v200 offset:1024
	ds_read_b128 v[192:195], v201 offset:1024
	s_waitcnt lgkmcnt(3)
	v_mfma_f32_16x16x32_bf16 v[94:97], v[146:149], v[154:157], v[94:97]
	v_mfma_f32_16x16x32_bf16 v[90:93], v[150:153], v[154:157], v[90:93]
	v_mfma_f32_16x16x32_bf16 v[86:89], v[158:161], v[154:157], v[86:89]
	v_mfma_f32_16x16x32_bf16 v[82:85], v[162:165], v[154:157], v[82:85]
	s_waitcnt lgkmcnt(2)
	v_mfma_f32_16x16x32_bf16 v[78:81], v[146:149], v[170:173], v[78:81]
	v_mfma_f32_16x16x32_bf16 v[74:77], v[150:153], v[170:173], v[74:77]
	v_mfma_f32_16x16x32_bf16 v[70:73], v[158:161], v[170:173], v[70:73]
	v_mfma_f32_16x16x32_bf16 v[66:69], v[162:165], v[170:173], v[66:69]
	ds_read_b128 v[154:157], v202 offset:1024
	ds_read_b128 v[170:173], v203 offset:1024
	s_waitcnt lgkmcnt(3)
	v_mfma_f32_16x16x32_bf16 v[62:65], v[146:149], v[166:169], v[62:65]
	v_mfma_f32_16x16x32_bf16 v[58:61], v[150:153], v[166:169], v[58:61]
	v_mfma_f32_16x16x32_bf16 v[54:57], v[158:161], v[166:169], v[54:57]
	v_mfma_f32_16x16x32_bf16 v[50:53], v[162:165], v[166:169], v[50:53]
	s_waitcnt lgkmcnt(2)
	v_mfma_f32_16x16x32_bf16 v[46:49], v[146:149], v[192:195], v[46:49]
	v_mfma_f32_16x16x32_bf16 v[42:45], v[150:153], v[192:195], v[42:45]
	v_mfma_f32_16x16x32_bf16 v[38:41], v[158:161], v[192:195], v[38:41]
	v_mfma_f32_16x16x32_bf16 v[34:37], v[162:165], v[192:195], v[34:37]
	s_waitcnt lgkmcnt(1)
	v_mfma_f32_16x16x32_bf16 v[30:33], v[146:149], v[154:157], v[30:33]
	v_mfma_f32_16x16x32_bf16 v[26:29], v[150:153], v[154:157], v[26:29]
	v_mfma_f32_16x16x32_bf16 v[22:25], v[158:161], v[154:157], v[22:25]
	v_mfma_f32_16x16x32_bf16 v[18:21], v[162:165], v[154:157], v[18:21]
	s_waitcnt lgkmcnt(0)
	v_mfma_f32_16x16x32_bf16 v[14:17], v[146:149], v[170:173], v[14:17]
	v_mfma_f32_16x16x32_bf16 v[10:13], v[150:153], v[170:173], v[10:13]
	v_mfma_f32_16x16x32_bf16 v[6:9], v[158:161], v[170:173], v[6:9]
	v_mfma_f32_16x16x32_bf16 v[2:5], v[162:165], v[170:173], v[2:5]
	s_add_u32 s6, s6, 0x80
	s_addc_u32 s7, s7, 0
	s_waitcnt vmcnt(0)
	s_add_u32 s2, s2, 0x80
	s_addc_u32 s3, s3, 0
	s_cmp_lg_u32 s9, 16
	s_barrier
	s_cbranch_scc0 .LBB0_200
	s_branch .LBB0_203

.LBB0_214:
	s_and_b32 s42, s30, 1
	s_lshl_b32 s29, s42, 16
	s_cmp_lt_u32 s30, 15
	s_cbranch_scc0 .LBB0_213
	s_add_i32 s16, s29, 0
	v_add3_u32 v149, s16, v134, v135
	ds_read_b128 v[150:153], v149 offset:32768
	ds_read_b128 v[154:157], v149 offset:34816
	ds_read_b128 v[162:165], v149 offset:36864
	ds_read_b128 v[166:169], v149 offset:38912
	v_add3_u32 v174, s16, v134, v140
	ds_read_b128 v[158:161], v174
	v_add3_u32 v175, s16, v142, v141
	v_add3_u32 v189, s16, v142, v143
	v_add3_u32 v198, s16, v142, v144
	ds_read_b128 v[170:173], v175
	s_waitcnt lgkmcnt(1)
	v_mfma_f32_16x16x32_bf16 v[126:129], v[150:153], v[158:161], v[126:129]
	v_add3_u32 v199, s16, v142, v145
	v_add3_u32 v200, s16, v142, v146
	v_add3_u32 v201, s16, v142, v147
	v_mfma_f32_16x16x32_bf16 v[122:125], v[154:157], v[158:161], v[122:125]
	v_add3_u32 v202, s16, v142, v148
	s_add_i32 s30, s30, 1
	v_mfma_f32_16x16x32_bf16 v[118:121], v[162:165], v[158:161], v[118:121]
	v_mfma_f32_16x16x32_bf16 v[114:117], v[166:169], v[158:161], v[114:117]
	ds_read_b128 v[158:161], v189
	ds_read_b128 v[190:193], v198
	s_lshl_b32 s29, s42, 16
	s_xor_b32 s16, s29, 0x10000
	s_add_i32 s17, s16, s40
	s_mov_b32 m0, s17
	s_nop 0
	global_load_lds_dwordx4 v130, s[10:11]
	s_waitcnt lgkmcnt(2)
	v_mfma_f32_16x16x32_bf16 v[110:113], v[150:153], v[170:173], v[110:113]
	v_mfma_f32_16x16x32_bf16 v[106:109], v[154:157], v[170:173], v[106:109]
	v_mfma_f32_16x16x32_bf16 v[102:105], v[162:165], v[170:173], v[102:105]
	v_mfma_f32_16x16x32_bf16 v[98:101], v[166:169], v[170:173], v[98:101]
	ds_read_b128 v[170:173], v199
	ds_read_b128 v[194:197], v200
	s_add_i32 s16, s16, s41
	s_mov_b32 m0, s16
	s_nop 0
	global_load_lds_dwordx4 v0, s[12:13]
	s_waitcnt lgkmcnt(3)
	v_mfma_f32_16x16x32_bf16 v[94:97], v[150:153], v[158:161], v[94:97]
	v_mfma_f32_16x16x32_bf16 v[90:93], v[154:157], v[158:161], v[90:93]
	v_mfma_f32_16x16x32_bf16 v[86:89], v[162:165], v[158:161], v[86:89]
	v_mfma_f32_16x16x32_bf16 v[82:85], v[166:169], v[158:161], v[82:85]
	s_xor_b32 s16, s29, 0x12000
	s_add_i32 s17, s16, s40
	s_add_i32 s39, s16, s41
	s_mov_b32 m0, s17
	s_nop 0
	global_load_lds_dwordx4 v131, s[10:11]
	s_waitcnt lgkmcnt(2)
	v_mfma_f32_16x16x32_bf16 v[78:81], v[150:153], v[190:193], v[78:81]
	v_mfma_f32_16x16x32_bf16 v[74:77], v[154:157], v[190:193], v[74:77]
	v_mfma_f32_16x16x32_bf16 v[70:73], v[162:165], v[190:193], v[70:73]
	v_mfma_f32_16x16x32_bf16 v[66:69], v[166:169], v[190:193], v[66:69]
	ds_read_b128 v[158:161], v201
	ds_read_b128 v[190:193], v202
	s_add_u32 s16, s12, 0x20000
	s_addc_u32 s17, s13, 0
	s_mov_b32 m0, s39
	s_nop 0
	global_load_lds_dwordx4 v0, s[16:17]
	s_waitcnt lgkmcnt(3)
	v_mfma_f32_16x16x32_bf16 v[62:65], v[150:153], v[170:173], v[62:65]
	v_mfma_f32_16x16x32_bf16 v[58:61], v[154:157], v[170:173], v[58:61]
	v_mfma_f32_16x16x32_bf16 v[54:57], v[162:165], v[170:173], v[54:57]
	v_mfma_f32_16x16x32_bf16 v[50:53], v[166:169], v[170:173], v[50:53]
	s_xor_b32 s16, s29, 0x14000
	s_add_i32 s17, s16, s40
	s_add_i32 s39, s16, s41
	s_mov_b32 m0, s17
	s_nop 0
	global_load_lds_dwordx4 v132, s[10:11]
	s_waitcnt lgkmcnt(2)
	v_mfma_f32_16x16x32_bf16 v[46:49], v[150:153], v[194:197], v[46:49]
	v_mfma_f32_16x16x32_bf16 v[42:45], v[154:157], v[194:197], v[42:45]
	v_mfma_f32_16x16x32_bf16 v[38:41], v[162:165], v[194:197], v[38:41]
	v_mfma_f32_16x16x32_bf16 v[34:37], v[166:169], v[194:197], v[34:37]
	s_add_u32 s16, s12, 0x40000
	s_addc_u32 s17, s13, 0
	s_mov_b32 m0, s39
	s_nop 0
	global_load_lds_dwordx4 v0, s[16:17]
	s_waitcnt lgkmcnt(1)
	v_mfma_f32_16x16x32_bf16 v[30:33], v[150:153], v[158:161], v[30:33]
	v_mfma_f32_16x16x32_bf16 v[26:29], v[154:157], v[158:161], v[26:29]
	v_mfma_f32_16x16x32_bf16 v[22:25], v[162:165], v[158:161], v[22:25]
	v_mfma_f32_16x16x32_bf16 v[18:21], v[166:169], v[158:161], v[18:21]
	s_xor_b32 s16, s29, 0x16000
	s_add_i32 s17, s16, s40
	s_add_i32 s39, s16, s41
	s_mov_b32 m0, s17
	s_nop 0
	global_load_lds_dwordx4 v133, s[10:11]
	s_waitcnt lgkmcnt(0)
	v_mfma_f32_16x16x32_bf16 v[14:17], v[150:153], v[190:193], v[14:17]
	v_mfma_f32_16x16x32_bf16 v[10:13], v[154:157], v[190:193], v[10:13]
	v_mfma_f32_16x16x32_bf16 v[6:9], v[162:165], v[190:193], v[6:9]
	v_mfma_f32_16x16x32_bf16 v[2:5], v[166:169], v[190:193], v[2:5]
	ds_read_b128 v[150:153], v149 offset:33792
	ds_read_b128 v[154:157], v149 offset:35840
	ds_read_b128 v[162:165], v149 offset:37888
	ds_read_b128 v[166:169], v149 offset:39936
	ds_read_b128 v[158:161], v174 offset:1024
	ds_read_b128 v[170:173], v175 offset:1024
	s_add_u32 s16, s12, 0x60000
	s_addc_u32 s17, s13, 0
	s_mov_b32 m0, s39
	s_nop 0
	global_load_lds_dwordx4 v0, s[16:17]
	s_waitcnt lgkmcnt(1)
	v_mfma_f32_16x16x32_bf16 v[126:129], v[150:153], v[158:161], v[126:129]
	v_mfma_f32_16x16x32_bf16 v[122:125], v[154:157], v[158:161], v[122:125]
	v_mfma_f32_16x16x32_bf16 v[118:121], v[162:165], v[158:161], v[118:121]
	v_mfma_f32_16x16x32_bf16 v[114:117], v[166:169], v[158:161], v[114:117]
	ds_read_b128 v[158:161], v189 offset:1024
	ds_read_b128 v[190:193], v198 offset:1024
	s_waitcnt lgkmcnt(2)
	v_mfma_f32_16x16x32_bf16 v[110:113], v[150:153], v[170:173], v[110:113]
	v_mfma_f32_16x16x32_bf16 v[106:109], v[154:157], v[170:173], v[106:109]
	v_mfma_f32_16x16x32_bf16 v[102:105], v[162:165], v[170:173], v[102:105]
	v_mfma_f32_16x16x32_bf16 v[98:101], v[166:169], v[170:173], v[98:101]
	ds_read_b128 v[170:173], v199 offset:1024
	ds_read_b128 v[194:197], v200 offset:1024
	s_waitcnt lgkmcnt(3)
	v_mfma_f32_16x16x32_bf16 v[94:97], v[150:153], v[158:161], v[94:97]
	v_mfma_f32_16x16x32_bf16 v[90:93], v[154:157], v[158:161], v[90:93]
	v_mfma_f32_16x16x32_bf16 v[86:89], v[162:165], v[158:161], v[86:89]
	v_mfma_f32_16x16x32_bf16 v[82:85], v[166:169], v[158:161], v[82:85]
	s_waitcnt lgkmcnt(2)
	v_mfma_f32_16x16x32_bf16 v[78:81], v[150:153], v[190:193], v[78:81]
	v_mfma_f32_16x16x32_bf16 v[74:77], v[154:157], v[190:193], v[74:77]
	v_mfma_f32_16x16x32_bf16 v[70:73], v[162:165], v[190:193], v[70:73]
	v_mfma_f32_16x16x32_bf16 v[66:69], v[166:169], v[190:193], v[66:69]
	ds_read_b128 v[158:161], v201 offset:1024
	ds_read_b128 v[190:193], v202 offset:1024
	s_waitcnt lgkmcnt(3)
	v_mfma_f32_16x16x32_bf16 v[62:65], v[150:153], v[170:173], v[62:65]
	v_mfma_f32_16x16x32_bf16 v[58:61], v[154:157], v[170:173], v[58:61]
	v_mfma_f32_16x16x32_bf16 v[54:57], v[162:165], v[170:173], v[54:57]
	v_mfma_f32_16x16x32_bf16 v[50:53], v[166:169], v[170:173], v[50:53]
	s_waitcnt lgkmcnt(2)
	v_mfma_f32_16x16x32_bf16 v[46:49], v[150:153], v[194:197], v[46:49]
	v_mfma_f32_16x16x32_bf16 v[42:45], v[154:157], v[194:197], v[42:45]
	v_mfma_f32_16x16x32_bf16 v[38:41], v[162:165], v[194:197], v[38:41]
	v_mfma_f32_16x16x32_bf16 v[34:37], v[166:169], v[194:197], v[34:37]
	s_waitcnt lgkmcnt(1)
	v_mfma_f32_16x16x32_bf16 v[30:33], v[150:153], v[158:161], v[30:33]
	v_mfma_f32_16x16x32_bf16 v[26:29], v[154:157], v[158:161], v[26:29]
	v_mfma_f32_16x16x32_bf16 v[22:25], v[162:165], v[158:161], v[22:25]
	v_mfma_f32_16x16x32_bf16 v[18:21], v[166:169], v[158:161], v[18:21]
	s_waitcnt lgkmcnt(0)
	v_mfma_f32_16x16x32_bf16 v[14:17], v[150:153], v[190:193], v[14:17]
	v_mfma_f32_16x16x32_bf16 v[10:13], v[154:157], v[190:193], v[10:13]
	v_mfma_f32_16x16x32_bf16 v[6:9], v[162:165], v[190:193], v[6:9]
	v_mfma_f32_16x16x32_bf16 v[2:5], v[166:169], v[190:193], v[2:5]
	s_add_u32 s12, s12, 0x80
	s_addc_u32 s13, s13, 0
	s_waitcnt vmcnt(0)
	s_add_u32 s10, s10, 0x80
	s_addc_u32 s11, s11, 0
	s_cmp_lg_u32 s30, 16
	s_barrier
	s_cbranch_scc0 .LBB0_211
	s_branch .LBB0_214

.LBB0_225:
	s_and_b32 s42, s21, 1
	s_lshl_b32 s29, s42, 16
	s_cmp_lt_u32 s21, 15
	s_cbranch_scc0 .LBB0_224
	s_add_i32 s8, s29, 0
	v_add3_u32 v145, s8, v134, v135
	ds_read_b128 v[146:149], v145 offset:32768
	ds_read_b128 v[156:159], v145 offset:34816
	ds_read_b128 v[164:167], v145 offset:36864
	ds_read_b128 v[168:171], v145 offset:38912
	v_add3_u32 v150, s8, v134, v136
	ds_read_b128 v[160:163], v150
	v_add3_u32 v151, s8, v138, v137
	v_add3_u32 v189, s8, v138, v139
	v_add3_u32 v198, s8, v138, v140
	ds_read_b128 v[172:175], v151
	s_waitcnt lgkmcnt(1)
	v_mfma_f32_16x16x32_bf16 v[126:129], v[146:149], v[160:163], v[126:129]
	v_add3_u32 v199, s8, v138, v141
	v_add3_u32 v200, s8, v138, v142
	v_add3_u32 v201, s8, v138, v143
	v_mfma_f32_16x16x32_bf16 v[122:125], v[156:159], v[160:163], v[122:125]
	v_add3_u32 v202, s8, v138, v144
	s_add_i32 s21, s21, 1
	v_mfma_f32_16x16x32_bf16 v[118:121], v[164:167], v[160:163], v[118:121]
	v_mfma_f32_16x16x32_bf16 v[114:117], v[168:171], v[160:163], v[114:117]
	ds_read_b128 v[160:163], v189
	ds_read_b128 v[190:193], v198
	s_lshl_b32 s29, s42, 16
	s_xor_b32 s8, s29, 0x10000
	s_add_i32 s9, s8, s25
	s_mov_b32 m0, s9
	s_nop 0
	global_load_lds_dwordx4 v130, s[2:3]
	s_waitcnt lgkmcnt(2)
	v_mfma_f32_16x16x32_bf16 v[110:113], v[146:149], v[172:175], v[110:113]
	v_mfma_f32_16x16x32_bf16 v[106:109], v[156:159], v[172:175], v[106:109]
	v_mfma_f32_16x16x32_bf16 v[102:105], v[164:167], v[172:175], v[102:105]
	v_mfma_f32_16x16x32_bf16 v[98:101], v[168:171], v[172:175], v[98:101]
	ds_read_b128 v[172:175], v199
	ds_read_b128 v[194:197], v200
	s_add_i32 s8, s8, s30
	s_mov_b32 m0, s8
	s_nop 0
	global_load_lds_dwordx4 v0, s[6:7]
	s_waitcnt lgkmcnt(3)
	v_mfma_f32_16x16x32_bf16 v[94:97], v[146:149], v[160:163], v[94:97]
	v_mfma_f32_16x16x32_bf16 v[90:93], v[156:159], v[160:163], v[90:93]
	v_mfma_f32_16x16x32_bf16 v[86:89], v[164:167], v[160:163], v[86:89]
	v_mfma_f32_16x16x32_bf16 v[82:85], v[168:171], v[160:163], v[82:85]
	s_xor_b32 s8, s29, 0x12000
	s_add_i32 s9, s8, s25
	s_add_i32 s39, s8, s30
	s_mov_b32 m0, s9
	s_nop 0
	global_load_lds_dwordx4 v131, s[2:3]
	s_waitcnt lgkmcnt(2)
	v_mfma_f32_16x16x32_bf16 v[78:81], v[146:149], v[190:193], v[78:81]
	v_mfma_f32_16x16x32_bf16 v[74:77], v[156:159], v[190:193], v[74:77]
	v_mfma_f32_16x16x32_bf16 v[70:73], v[164:167], v[190:193], v[70:73]
	v_mfma_f32_16x16x32_bf16 v[66:69], v[168:171], v[190:193], v[66:69]
	ds_read_b128 v[160:163], v201
	ds_read_b128 v[190:193], v202
	s_add_u32 s8, s6, 0x20000
	s_addc_u32 s9, s7, 0
	s_mov_b32 m0, s39
	s_nop 0
	global_load_lds_dwordx4 v0, s[8:9]
	s_waitcnt lgkmcnt(3)
	v_mfma_f32_16x16x32_bf16 v[62:65], v[146:149], v[172:175], v[62:65]
	v_mfma_f32_16x16x32_bf16 v[58:61], v[156:159], v[172:175], v[58:61]
	v_mfma_f32_16x16x32_bf16 v[54:57], v[164:167], v[172:175], v[54:57]
	v_mfma_f32_16x16x32_bf16 v[50:53], v[168:171], v[172:175], v[50:53]
	s_xor_b32 s8, s29, 0x14000
	s_add_i32 s9, s8, s25
	s_add_i32 s39, s8, s30
	s_mov_b32 m0, s9
	s_nop 0
	global_load_lds_dwordx4 v132, s[2:3]
	s_waitcnt lgkmcnt(2)
	v_mfma_f32_16x16x32_bf16 v[46:49], v[146:149], v[194:197], v[46:49]
	v_mfma_f32_16x16x32_bf16 v[42:45], v[156:159], v[194:197], v[42:45]
	v_mfma_f32_16x16x32_bf16 v[38:41], v[164:167], v[194:197], v[38:41]
	v_mfma_f32_16x16x32_bf16 v[34:37], v[168:171], v[194:197], v[34:37]
	s_add_u32 s8, s6, 0x40000
	s_addc_u32 s9, s7, 0
	s_mov_b32 m0, s39
	s_nop 0
	global_load_lds_dwordx4 v0, s[8:9]
	s_waitcnt lgkmcnt(1)
	v_mfma_f32_16x16x32_bf16 v[30:33], v[146:149], v[160:163], v[30:33]
	v_mfma_f32_16x16x32_bf16 v[26:29], v[156:159], v[160:163], v[26:29]
	v_mfma_f32_16x16x32_bf16 v[22:25], v[164:167], v[160:163], v[22:25]
	v_mfma_f32_16x16x32_bf16 v[18:21], v[168:171], v[160:163], v[18:21]
	s_xor_b32 s8, s29, 0x16000
	s_add_i32 s9, s8, s25
	s_add_i32 s39, s8, s30
	s_mov_b32 m0, s9
	s_nop 0
	global_load_lds_dwordx4 v133, s[2:3]
	s_waitcnt lgkmcnt(0)
	v_mfma_f32_16x16x32_bf16 v[14:17], v[146:149], v[190:193], v[14:17]
	v_mfma_f32_16x16x32_bf16 v[10:13], v[156:159], v[190:193], v[10:13]
	v_mfma_f32_16x16x32_bf16 v[6:9], v[164:167], v[190:193], v[6:9]
	v_mfma_f32_16x16x32_bf16 v[2:5], v[168:171], v[190:193], v[2:5]
	ds_read_b128 v[146:149], v145 offset:33792
	ds_read_b128 v[156:159], v145 offset:35840
	ds_read_b128 v[164:167], v145 offset:37888
	ds_read_b128 v[168:171], v145 offset:39936
	ds_read_b128 v[160:163], v150 offset:1024
	ds_read_b128 v[172:175], v151 offset:1024
	s_add_u32 s8, s6, 0x60000
	s_addc_u32 s9, s7, 0
	s_mov_b32 m0, s39
	s_nop 0
	global_load_lds_dwordx4 v0, s[8:9]
	s_waitcnt lgkmcnt(1)
	v_mfma_f32_16x16x32_bf16 v[126:129], v[146:149], v[160:163], v[126:129]
	v_mfma_f32_16x16x32_bf16 v[122:125], v[156:159], v[160:163], v[122:125]
	v_mfma_f32_16x16x32_bf16 v[118:121], v[164:167], v[160:163], v[118:121]
	v_mfma_f32_16x16x32_bf16 v[114:117], v[168:171], v[160:163], v[114:117]
	ds_read_b128 v[160:163], v189 offset:1024
	ds_read_b128 v[190:193], v198 offset:1024
	s_waitcnt lgkmcnt(2)
	v_mfma_f32_16x16x32_bf16 v[110:113], v[146:149], v[172:175], v[110:113]
	v_mfma_f32_16x16x32_bf16 v[106:109], v[156:159], v[172:175], v[106:109]
	v_mfma_f32_16x16x32_bf16 v[102:105], v[164:167], v[172:175], v[102:105]
	v_mfma_f32_16x16x32_bf16 v[98:101], v[168:171], v[172:175], v[98:101]
	ds_read_b128 v[172:175], v199 offset:1024
	ds_read_b128 v[194:197], v200 offset:1024
	s_waitcnt lgkmcnt(3)
	v_mfma_f32_16x16x32_bf16 v[94:97], v[146:149], v[160:163], v[94:97]
	v_mfma_f32_16x16x32_bf16 v[90:93], v[156:159], v[160:163], v[90:93]
	v_mfma_f32_16x16x32_bf16 v[86:89], v[164:167], v[160:163], v[86:89]
	v_mfma_f32_16x16x32_bf16 v[82:85], v[168:171], v[160:163], v[82:85]
	s_waitcnt lgkmcnt(2)
	v_mfma_f32_16x16x32_bf16 v[78:81], v[146:149], v[190:193], v[78:81]
	v_mfma_f32_16x16x32_bf16 v[74:77], v[156:159], v[190:193], v[74:77]
	v_mfma_f32_16x16x32_bf16 v[70:73], v[164:167], v[190:193], v[70:73]
	v_mfma_f32_16x16x32_bf16 v[66:69], v[168:171], v[190:193], v[66:69]
	ds_read_b128 v[160:163], v201 offset:1024
	ds_read_b128 v[190:193], v202 offset:1024
	s_waitcnt lgkmcnt(3)
	v_mfma_f32_16x16x32_bf16 v[62:65], v[146:149], v[172:175], v[62:65]
	v_mfma_f32_16x16x32_bf16 v[58:61], v[156:159], v[172:175], v[58:61]
	v_mfma_f32_16x16x32_bf16 v[54:57], v[164:167], v[172:175], v[54:57]
	v_mfma_f32_16x16x32_bf16 v[50:53], v[168:171], v[172:175], v[50:53]
	s_waitcnt lgkmcnt(2)
	v_mfma_f32_16x16x32_bf16 v[46:49], v[146:149], v[194:197], v[46:49]
	v_mfma_f32_16x16x32_bf16 v[42:45], v[156:159], v[194:197], v[42:45]
	v_mfma_f32_16x16x32_bf16 v[38:41], v[164:167], v[194:197], v[38:41]
	v_mfma_f32_16x16x32_bf16 v[34:37], v[168:171], v[194:197], v[34:37]
	s_waitcnt lgkmcnt(1)
	v_mfma_f32_16x16x32_bf16 v[30:33], v[146:149], v[160:163], v[30:33]
	v_mfma_f32_16x16x32_bf16 v[26:29], v[156:159], v[160:163], v[26:29]
	v_mfma_f32_16x16x32_bf16 v[22:25], v[164:167], v[160:163], v[22:25]
	v_mfma_f32_16x16x32_bf16 v[18:21], v[168:171], v[160:163], v[18:21]
	s_waitcnt lgkmcnt(0)
	v_mfma_f32_16x16x32_bf16 v[14:17], v[146:149], v[190:193], v[14:17]
	v_mfma_f32_16x16x32_bf16 v[10:13], v[156:159], v[190:193], v[10:13]
	v_mfma_f32_16x16x32_bf16 v[6:9], v[164:167], v[190:193], v[6:9]
	v_mfma_f32_16x16x32_bf16 v[2:5], v[168:171], v[190:193], v[2:5]
	s_add_u32 s6, s6, 0x80
	s_addc_u32 s7, s7, 0
	s_waitcnt vmcnt(0)
	s_add_u32 s2, s2, 0x80
	s_addc_u32 s3, s3, 0
	s_cmp_lg_u32 s21, 16
	s_barrier
	s_cbranch_scc0 .LBB0_229
	s_branch .LBB0_225

.LBB0_307:
	s_and_b32 s29, s19, 1
	s_lshl_b32 s25, s29, 16
	s_cmp_lt_u32 s19, 15
	s_cbranch_scc0 .LBB0_306
	s_add_i32 s20, s25, 0
	v_add3_u32 v174, s20, v135, v136
	ds_read_b128 v[146:149], v174 offset:32768
	ds_read_b128 v[150:153], v174 offset:34816
	ds_read_b128 v[158:161], v174 offset:36864
	ds_read_b128 v[162:165], v174 offset:38912
	v_add3_u32 v175, s20, v135, v137
	ds_read_b128 v[154:157], v175
	v_add3_u32 v189, s20, v138, v139
	v_add3_u32 v198, s20, v138, v140
	v_add3_u32 v199, s20, v138, v141
	ds_read_b128 v[170:173], v189
	s_waitcnt lgkmcnt(1)
	v_mfma_f32_16x16x32_bf16 v[126:129], v[146:149], v[154:157], v[126:129]
	v_add3_u32 v200, s20, v138, v142
	v_add3_u32 v201, s20, v138, v143
	v_add3_u32 v202, s20, v138, v144
	v_mfma_f32_16x16x32_bf16 v[122:125], v[150:153], v[154:157], v[122:125]
	v_add3_u32 v203, s20, v138, v145
	s_add_i32 s19, s19, 1
	v_mfma_f32_16x16x32_bf16 v[118:121], v[158:161], v[154:157], v[118:121]
	v_mfma_f32_16x16x32_bf16 v[114:117], v[162:165], v[154:157], v[114:117]
	ds_read_b128 v[154:157], v198
	ds_read_b128 v[190:193], v199
	s_lshl_b32 s25, s29, 16
	s_xor_b32 s20, s25, 0x10000
	s_add_i32 s21, s20, s23
	s_mov_b32 m0, s21
	s_nop 0
	global_load_lds_dwordx4 v131, s[42:43]
	s_waitcnt lgkmcnt(2)
	v_mfma_f32_16x16x32_bf16 v[110:113], v[146:149], v[170:173], v[110:113]
	v_mfma_f32_16x16x32_bf16 v[106:109], v[150:153], v[170:173], v[106:109]
	v_mfma_f32_16x16x32_bf16 v[102:105], v[158:161], v[170:173], v[102:105]
	v_mfma_f32_16x16x32_bf16 v[98:101], v[162:165], v[170:173], v[98:101]
	ds_read_b128 v[170:173], v200
	ds_read_b128 v[194:197], v201
	s_add_i32 s20, s20, s24
	s_mov_b32 m0, s20
	s_nop 0
	global_load_lds_dwordx4 v130, s[44:45]
	s_waitcnt lgkmcnt(3)
	v_mfma_f32_16x16x32_bf16 v[94:97], v[146:149], v[154:157], v[94:97]
	v_mfma_f32_16x16x32_bf16 v[90:93], v[150:153], v[154:157], v[90:93]
	v_mfma_f32_16x16x32_bf16 v[86:89], v[158:161], v[154:157], v[86:89]
	v_mfma_f32_16x16x32_bf16 v[82:85], v[162:165], v[154:157], v[82:85]
	s_xor_b32 s20, s25, 0x12000
	s_add_i32 s21, s20, s23
	s_add_i32 s29, s20, s24
	s_mov_b32 m0, s21
	s_nop 0
	global_load_lds_dwordx4 v132, s[42:43]
	s_waitcnt lgkmcnt(2)
	v_mfma_f32_16x16x32_bf16 v[78:81], v[146:149], v[190:193], v[78:81]
	v_mfma_f32_16x16x32_bf16 v[74:77], v[150:153], v[190:193], v[74:77]
	v_mfma_f32_16x16x32_bf16 v[70:73], v[158:161], v[190:193], v[70:73]
	v_mfma_f32_16x16x32_bf16 v[66:69], v[162:165], v[190:193], v[66:69]
	ds_read_b128 v[154:157], v202
	ds_read_b128 v[190:193], v203
	s_add_u32 s20, s44, 0x20000
	s_addc_u32 s21, s45, 0
	s_mov_b32 m0, s29
	s_nop 0
	global_load_lds_dwordx4 v130, s[20:21]
	s_waitcnt lgkmcnt(3)
	v_mfma_f32_16x16x32_bf16 v[62:65], v[146:149], v[170:173], v[62:65]
	v_mfma_f32_16x16x32_bf16 v[58:61], v[150:153], v[170:173], v[58:61]
	v_mfma_f32_16x16x32_bf16 v[54:57], v[158:161], v[170:173], v[54:57]
	v_mfma_f32_16x16x32_bf16 v[50:53], v[162:165], v[170:173], v[50:53]
	s_xor_b32 s20, s25, 0x14000
	s_add_i32 s21, s20, s23
	s_add_i32 s29, s20, s24
	s_mov_b32 m0, s21
	s_nop 0
	global_load_lds_dwordx4 v133, s[42:43]
	s_waitcnt lgkmcnt(2)
	v_mfma_f32_16x16x32_bf16 v[46:49], v[146:149], v[194:197], v[46:49]
	v_mfma_f32_16x16x32_bf16 v[42:45], v[150:153], v[194:197], v[42:45]
	v_mfma_f32_16x16x32_bf16 v[38:41], v[158:161], v[194:197], v[38:41]
	v_mfma_f32_16x16x32_bf16 v[34:37], v[162:165], v[194:197], v[34:37]
	s_add_u32 s20, s44, 0x40000
	s_addc_u32 s21, s45, 0
	s_mov_b32 m0, s29
	s_nop 0
	global_load_lds_dwordx4 v130, s[20:21]
	s_waitcnt lgkmcnt(1)
	v_mfma_f32_16x16x32_bf16 v[30:33], v[146:149], v[154:157], v[30:33]
	v_mfma_f32_16x16x32_bf16 v[26:29], v[150:153], v[154:157], v[26:29]
	v_mfma_f32_16x16x32_bf16 v[22:25], v[158:161], v[154:157], v[22:25]
	v_mfma_f32_16x16x32_bf16 v[18:21], v[162:165], v[154:157], v[18:21]
	s_xor_b32 s20, s25, 0x16000
	s_add_i32 s21, s20, s23
	s_add_i32 s29, s20, s24
	s_mov_b32 m0, s21
	s_nop 0
	global_load_lds_dwordx4 v134, s[42:43]
	s_waitcnt lgkmcnt(0)
	v_mfma_f32_16x16x32_bf16 v[14:17], v[146:149], v[190:193], v[14:17]
	v_mfma_f32_16x16x32_bf16 v[10:13], v[150:153], v[190:193], v[10:13]
	v_mfma_f32_16x16x32_bf16 v[6:9], v[158:161], v[190:193], v[6:9]
	v_mfma_f32_16x16x32_bf16 v[2:5], v[162:165], v[190:193], v[2:5]
	ds_read_b128 v[146:149], v174 offset:33792
	ds_read_b128 v[150:153], v174 offset:35840
	ds_read_b128 v[158:161], v174 offset:37888
	ds_read_b128 v[162:165], v174 offset:39936
	ds_read_b128 v[154:157], v175 offset:1024
	ds_read_b128 v[170:173], v189 offset:1024
	s_add_u32 s20, s44, 0x60000
	s_addc_u32 s21, s45, 0
	s_mov_b32 m0, s29
	s_nop 0
	global_load_lds_dwordx4 v130, s[20:21]
	s_waitcnt lgkmcnt(1)
	v_mfma_f32_16x16x32_bf16 v[126:129], v[146:149], v[154:157], v[126:129]
	v_mfma_f32_16x16x32_bf16 v[122:125], v[150:153], v[154:157], v[122:125]
	v_mfma_f32_16x16x32_bf16 v[118:121], v[158:161], v[154:157], v[118:121]
	v_mfma_f32_16x16x32_bf16 v[114:117], v[162:165], v[154:157], v[114:117]
	ds_read_b128 v[154:157], v198 offset:1024
	ds_read_b128 v[190:193], v199 offset:1024
	s_waitcnt lgkmcnt(2)
	v_mfma_f32_16x16x32_bf16 v[110:113], v[146:149], v[170:173], v[110:113]
	v_mfma_f32_16x16x32_bf16 v[106:109], v[150:153], v[170:173], v[106:109]
	v_mfma_f32_16x16x32_bf16 v[102:105], v[158:161], v[170:173], v[102:105]
	v_mfma_f32_16x16x32_bf16 v[98:101], v[162:165], v[170:173], v[98:101]
	ds_read_b128 v[170:173], v200 offset:1024
	ds_read_b128 v[194:197], v201 offset:1024
	s_waitcnt lgkmcnt(3)
	v_mfma_f32_16x16x32_bf16 v[94:97], v[146:149], v[154:157], v[94:97]
	v_mfma_f32_16x16x32_bf16 v[90:93], v[150:153], v[154:157], v[90:93]
	v_mfma_f32_16x16x32_bf16 v[86:89], v[158:161], v[154:157], v[86:89]
	v_mfma_f32_16x16x32_bf16 v[82:85], v[162:165], v[154:157], v[82:85]
	s_waitcnt lgkmcnt(2)
	v_mfma_f32_16x16x32_bf16 v[78:81], v[146:149], v[190:193], v[78:81]
	v_mfma_f32_16x16x32_bf16 v[74:77], v[150:153], v[190:193], v[74:77]
	v_mfma_f32_16x16x32_bf16 v[70:73], v[158:161], v[190:193], v[70:73]
	v_mfma_f32_16x16x32_bf16 v[66:69], v[162:165], v[190:193], v[66:69]
	ds_read_b128 v[154:157], v202 offset:1024
	ds_read_b128 v[190:193], v203 offset:1024
	s_waitcnt lgkmcnt(3)
	v_mfma_f32_16x16x32_bf16 v[62:65], v[146:149], v[170:173], v[62:65]
	v_mfma_f32_16x16x32_bf16 v[58:61], v[150:153], v[170:173], v[58:61]
	v_mfma_f32_16x16x32_bf16 v[54:57], v[158:161], v[170:173], v[54:57]
	v_mfma_f32_16x16x32_bf16 v[50:53], v[162:165], v[170:173], v[50:53]
	s_waitcnt lgkmcnt(2)
	v_mfma_f32_16x16x32_bf16 v[46:49], v[146:149], v[194:197], v[46:49]
	v_mfma_f32_16x16x32_bf16 v[42:45], v[150:153], v[194:197], v[42:45]
	v_mfma_f32_16x16x32_bf16 v[38:41], v[158:161], v[194:197], v[38:41]
	v_mfma_f32_16x16x32_bf16 v[34:37], v[162:165], v[194:197], v[34:37]
	s_waitcnt lgkmcnt(1)
	v_mfma_f32_16x16x32_bf16 v[30:33], v[146:149], v[154:157], v[30:33]
	v_mfma_f32_16x16x32_bf16 v[26:29], v[150:153], v[154:157], v[26:29]
	v_mfma_f32_16x16x32_bf16 v[22:25], v[158:161], v[154:157], v[22:25]
	v_mfma_f32_16x16x32_bf16 v[18:21], v[162:165], v[154:157], v[18:21]
	s_waitcnt lgkmcnt(0)
	v_mfma_f32_16x16x32_bf16 v[14:17], v[146:149], v[190:193], v[14:17]
	v_mfma_f32_16x16x32_bf16 v[10:13], v[150:153], v[190:193], v[10:13]
	v_mfma_f32_16x16x32_bf16 v[6:9], v[158:161], v[190:193], v[6:9]
	v_mfma_f32_16x16x32_bf16 v[2:5], v[162:165], v[190:193], v[2:5]
	s_add_u32 s44, s44, 0x80
	s_addc_u32 s45, s45, 0
	s_waitcnt vmcnt(0)
	s_add_u32 s42, s42, 0x80
	s_addc_u32 s43, s43, 0
	s_cmp_lg_u32 s19, 16
	s_barrier
	s_cbranch_scc0 .LBB0_311
	s_branch .LBB0_307

.LBB0_632:
	s_and_b32 s29, s11, 1
	s_add_i32 s11, s11, 1
	s_lshl_b32 s25, s29, 16
	s_cmp_lt_u32 s11, s16
	s_cbranch_scc0 .LBB0_631
	s_add_i32 s12, s25, 0
	v_add3_u32 v146, s12, v135, v136
	ds_read_b128 v[152:155], v146 offset:32768
	ds_read_b128 v[156:159], v146 offset:34816
	ds_read_b128 v[164:167], v146 offset:36864
	ds_read_b128 v[168:171], v146 offset:38912
	v_add3_u32 v147, s12, v135, v137
	ds_read_b128 v[160:163], v147
	v_add3_u32 v189, s12, v139, v138
	v_add3_u32 v198, s12, v139, v140
	v_add3_u32 v199, s12, v139, v141
	ds_read_b128 v[172:175], v189
	s_waitcnt lgkmcnt(1)
	v_mfma_f32_16x16x32_bf16 v[126:129], v[152:155], v[160:163], v[126:129]
	v_add3_u32 v200, s12, v139, v142
	v_add3_u32 v201, s12, v139, v143
	v_add3_u32 v202, s12, v139, v144
	v_mfma_f32_16x16x32_bf16 v[122:125], v[156:159], v[160:163], v[122:125]
	v_add3_u32 v203, s12, v139, v145
	v_mfma_f32_16x16x32_bf16 v[118:121], v[164:167], v[160:163], v[118:121]
	v_mfma_f32_16x16x32_bf16 v[114:117], v[168:171], v[160:163], v[114:117]
	ds_read_b128 v[160:163], v198
	ds_read_b128 v[190:193], v199
	s_lshl_b64 s[12:13], s[86:87], 1
	s_add_u32 s40, s2, s12
	s_addc_u32 s41, s3, s13
	s_add_u32 s12, s4, s12
	s_addc_u32 s13, s5, s13
	s_lshl_b32 s25, s29, 16
	s_xor_b32 s29, s25, 0x10000
	s_add_i32 s30, s29, s23
	s_mov_b32 m0, s30
	s_nop 0
	global_load_lds_dwordx4 v131, s[40:41]
	s_waitcnt lgkmcnt(2)
	v_mfma_f32_16x16x32_bf16 v[110:113], v[152:155], v[172:175], v[110:113]
	v_mfma_f32_16x16x32_bf16 v[106:109], v[156:159], v[172:175], v[106:109]
	v_mfma_f32_16x16x32_bf16 v[102:105], v[164:167], v[172:175], v[102:105]
	v_mfma_f32_16x16x32_bf16 v[98:101], v[168:171], v[172:175], v[98:101]
	ds_read_b128 v[172:175], v200
	ds_read_b128 v[194:197], v201
	s_add_i32 s29, s29, s24
	s_mov_b32 m0, s29
	s_nop 0
	global_load_lds_dwordx4 v130, s[12:13]
	s_waitcnt lgkmcnt(3)
	v_mfma_f32_16x16x32_bf16 v[94:97], v[152:155], v[160:163], v[94:97]
	v_mfma_f32_16x16x32_bf16 v[90:93], v[156:159], v[160:163], v[90:93]
	v_mfma_f32_16x16x32_bf16 v[86:89], v[164:167], v[160:163], v[86:89]
	v_mfma_f32_16x16x32_bf16 v[82:85], v[168:171], v[160:163], v[82:85]
	s_xor_b32 s29, s25, 0x12000
	s_add_i32 s30, s29, s23
	s_add_i32 s29, s29, s24
	s_mov_b32 m0, s30
	s_nop 0
	global_load_lds_dwordx4 v132, s[40:41]
	s_waitcnt lgkmcnt(2)
	v_mfma_f32_16x16x32_bf16 v[78:81], v[152:155], v[190:193], v[78:81]
	v_mfma_f32_16x16x32_bf16 v[74:77], v[156:159], v[190:193], v[74:77]
	v_mfma_f32_16x16x32_bf16 v[70:73], v[164:167], v[190:193], v[70:73]
	v_mfma_f32_16x16x32_bf16 v[66:69], v[168:171], v[190:193], v[66:69]
	ds_read_b128 v[160:163], v202
	ds_read_b128 v[190:193], v203
	s_add_u32 s42, s12, s17
	s_addc_u32 s43, s13, 0
	s_mov_b32 m0, s29
	s_nop 0
	global_load_lds_dwordx4 v130, s[42:43]
	s_waitcnt lgkmcnt(3)
	v_mfma_f32_16x16x32_bf16 v[62:65], v[152:155], v[172:175], v[62:65]
	v_mfma_f32_16x16x32_bf16 v[58:61], v[156:159], v[172:175], v[58:61]
	v_mfma_f32_16x16x32_bf16 v[54:57], v[164:167], v[172:175], v[54:57]
	v_mfma_f32_16x16x32_bf16 v[50:53], v[168:171], v[172:175], v[50:53]
	s_xor_b32 s29, s25, 0x14000
	s_add_i32 s30, s29, s23
	s_add_i32 s29, s29, s24
	s_mov_b32 m0, s30
	s_nop 0
	global_load_lds_dwordx4 v133, s[40:41]
	s_waitcnt lgkmcnt(2)
	v_mfma_f32_16x16x32_bf16 v[46:49], v[152:155], v[194:197], v[46:49]
	v_mfma_f32_16x16x32_bf16 v[42:45], v[156:159], v[194:197], v[42:45]
	v_mfma_f32_16x16x32_bf16 v[38:41], v[164:167], v[194:197], v[38:41]
	v_mfma_f32_16x16x32_bf16 v[34:37], v[168:171], v[194:197], v[34:37]
	s_add_u32 s42, s12, s19
	s_addc_u32 s43, s13, 0
	s_mov_b32 m0, s29
	s_nop 0
	global_load_lds_dwordx4 v130, s[42:43]
	s_waitcnt lgkmcnt(1)
	v_mfma_f32_16x16x32_bf16 v[30:33], v[152:155], v[160:163], v[30:33]
	v_mfma_f32_16x16x32_bf16 v[26:29], v[156:159], v[160:163], v[26:29]
	v_mfma_f32_16x16x32_bf16 v[22:25], v[164:167], v[160:163], v[22:25]
	v_mfma_f32_16x16x32_bf16 v[18:21], v[168:171], v[160:163], v[18:21]
	s_xor_b32 s29, s25, 0x16000
	s_add_i32 s30, s29, s23
	s_add_i32 s29, s29, s24
	s_mov_b32 m0, s30
	s_nop 0
	global_load_lds_dwordx4 v134, s[40:41]
	s_waitcnt lgkmcnt(0)
	v_mfma_f32_16x16x32_bf16 v[14:17], v[152:155], v[190:193], v[14:17]
	v_mfma_f32_16x16x32_bf16 v[10:13], v[156:159], v[190:193], v[10:13]
	v_mfma_f32_16x16x32_bf16 v[6:9], v[164:167], v[190:193], v[6:9]
	v_mfma_f32_16x16x32_bf16 v[2:5], v[168:171], v[190:193], v[2:5]
	ds_read_b128 v[152:155], v146 offset:33792
	ds_read_b128 v[156:159], v146 offset:35840
	ds_read_b128 v[164:167], v146 offset:37888
	ds_read_b128 v[168:171], v146 offset:39936
	ds_read_b128 v[160:163], v147 offset:1024
	ds_read_b128 v[172:175], v189 offset:1024
	s_add_u32 s12, s12, s20
	s_addc_u32 s13, s13, 0
	s_mov_b32 m0, s29
	s_nop 0
	global_load_lds_dwordx4 v130, s[12:13]
	s_waitcnt lgkmcnt(1)
	v_mfma_f32_16x16x32_bf16 v[126:129], v[152:155], v[160:163], v[126:129]
	v_mfma_f32_16x16x32_bf16 v[122:125], v[156:159], v[160:163], v[122:125]
	v_mfma_f32_16x16x32_bf16 v[118:121], v[164:167], v[160:163], v[118:121]
	v_mfma_f32_16x16x32_bf16 v[114:117], v[168:171], v[160:163], v[114:117]
	ds_read_b128 v[160:163], v198 offset:1024
	ds_read_b128 v[190:193], v199 offset:1024
	s_waitcnt lgkmcnt(2)
	v_mfma_f32_16x16x32_bf16 v[110:113], v[152:155], v[172:175], v[110:113]
	v_mfma_f32_16x16x32_bf16 v[106:109], v[156:159], v[172:175], v[106:109]
	v_mfma_f32_16x16x32_bf16 v[102:105], v[164:167], v[172:175], v[102:105]
	v_mfma_f32_16x16x32_bf16 v[98:101], v[168:171], v[172:175], v[98:101]
	ds_read_b128 v[172:175], v200 offset:1024
	ds_read_b128 v[194:197], v201 offset:1024
	s_waitcnt lgkmcnt(3)
	v_mfma_f32_16x16x32_bf16 v[94:97], v[152:155], v[160:163], v[94:97]
	v_mfma_f32_16x16x32_bf16 v[90:93], v[156:159], v[160:163], v[90:93]
	v_mfma_f32_16x16x32_bf16 v[86:89], v[164:167], v[160:163], v[86:89]
	v_mfma_f32_16x16x32_bf16 v[82:85], v[168:171], v[160:163], v[82:85]
	s_waitcnt lgkmcnt(2)
	v_mfma_f32_16x16x32_bf16 v[78:81], v[152:155], v[190:193], v[78:81]
	v_mfma_f32_16x16x32_bf16 v[74:77], v[156:159], v[190:193], v[74:77]
	v_mfma_f32_16x16x32_bf16 v[70:73], v[164:167], v[190:193], v[70:73]
	v_mfma_f32_16x16x32_bf16 v[66:69], v[168:171], v[190:193], v[66:69]
	ds_read_b128 v[160:163], v202 offset:1024
	ds_read_b128 v[190:193], v203 offset:1024
	s_waitcnt lgkmcnt(3)
	v_mfma_f32_16x16x32_bf16 v[62:65], v[152:155], v[172:175], v[62:65]
	v_mfma_f32_16x16x32_bf16 v[58:61], v[156:159], v[172:175], v[58:61]
	v_mfma_f32_16x16x32_bf16 v[54:57], v[164:167], v[172:175], v[54:57]
	v_mfma_f32_16x16x32_bf16 v[50:53], v[168:171], v[172:175], v[50:53]
	s_waitcnt lgkmcnt(2)
	v_mfma_f32_16x16x32_bf16 v[46:49], v[152:155], v[194:197], v[46:49]
	v_mfma_f32_16x16x32_bf16 v[42:45], v[156:159], v[194:197], v[42:45]
	v_mfma_f32_16x16x32_bf16 v[38:41], v[164:167], v[194:197], v[38:41]
	v_mfma_f32_16x16x32_bf16 v[34:37], v[168:171], v[194:197], v[34:37]
	s_waitcnt lgkmcnt(1)
	v_mfma_f32_16x16x32_bf16 v[30:33], v[152:155], v[160:163], v[30:33]
	v_mfma_f32_16x16x32_bf16 v[26:29], v[156:159], v[160:163], v[26:29]
	v_mfma_f32_16x16x32_bf16 v[22:25], v[164:167], v[160:163], v[22:25]
	v_mfma_f32_16x16x32_bf16 v[18:21], v[168:171], v[160:163], v[18:21]
	s_waitcnt lgkmcnt(0)
	v_mfma_f32_16x16x32_bf16 v[14:17], v[152:155], v[190:193], v[14:17]
	v_mfma_f32_16x16x32_bf16 v[10:13], v[156:159], v[190:193], v[10:13]
	v_mfma_f32_16x16x32_bf16 v[6:9], v[164:167], v[190:193], v[6:9]
	v_mfma_f32_16x16x32_bf16 v[2:5], v[168:171], v[190:193], v[2:5]
	s_waitcnt vmcnt(0)
	s_add_i32 s86, s86, 64
	s_cmp_lg_u32 s16, s11
	s_barrier
	s_cbranch_scc0 .LBB0_636
	s_branch .LBB0_632
